# attention: K rows of the next unit are requested during the P.V phase of the current one (rolling 32 rows in flight), q and index rows prefetched one unit ahead
# speedup vs baseline: 1.1241x; 1.0327x over previous
; #define LAS __attribute__((address_space(3)))
; __device__ __forceinline__ float bf_lo(unsigned v) { return __uint_as_float(v << 16); }
; __device__ __forceinline__ float bf_hi(unsigned v) { return __uint_as_float(v & 0xffff0000u); }
; __device__ __forceinline__ int lane_id() { int l; asm volatile("v_mbcnt_lo_u32_b32 %0, -1, 0\n\tv_mbcnt_hi_u32_b32 %0, -1, %0\n\ts_nop 1" : "=v"(l)); return l; }
; __device__ __forceinline__ void kv8_issue(u32x4 (&buf)[8], __amdgpu_buffer_rsrc_t rs, int voff  , int sbase  , const int (&iv)[4], int b) {
;     const int jj = b >> 3, l0 = (b & 7) * 8;
;     const int ivb = (jj == 0) ? iv[0] : (jj == 1) ? iv[1] : (jj == 2) ? iv[2] : iv[3];
; #pragma unroll
;     for (int u = 0; u < 8; ++u) { const int si = __builtin_amdgcn_readlane(ivb, l0 + u); buf[u] = __builtin_amdgcn_raw_buffer_load_b128(rs, voff, si * 2048 + sbase, KV8_AUX); }
; __device__ __forceinline__ void attn_query8(const unsigned char* __restrict__ KV8, const bf16_t* __restrict__ Z, const int* __restrict__ SEL, bf16_t* __restrict__ YMIX, int t, LAS float* sbuf  ) {
;     const int lane = lane_id(), hd = lane >> 3;
;     const int nsel = (t + 1 < 256) ? (t + 1) : 256, nb = (nsel + 7) >> 3;
;     int iv[4];
; #pragma unroll
;     for (int jj = 0; jj < 4; ++jj) { const int e = lane + 64 * jj; iv[jj] = (e < nsel) ? SEL[(size_t)t * 256 + e] : 0; }
;     f32x2v qf[8];
;     { const u32x4* qp = (const u32x4*)(Z + (size_t)t * ZLD + OFF_Q + lane * 16); const u32x4 a = qp[0], b = qp[1];
;       qf[0] = (f32x2v){bf_lo(a.x), bf_hi(a.x)}; qf[1] = (f32x2v){bf_lo(a.y), bf_hi(a.y)}; qf[2] = (f32x2v){bf_lo(a.z), bf_hi(a.z)}; qf[3] = (f32x2v){bf_lo(a.w), bf_hi(a.w)};
;       qf[4] = (f32x2v){bf_lo(b.x), bf_hi(b.x)}; qf[5] = (f32x2v){bf_lo(b.y), bf_hi(b.y)}; qf[6] = (f32x2v){bf_lo(b.z), bf_hi(b.z)}; qf[7] = (f32x2v){bf_lo(b.w), bf_hi(b.w)}; }
;     const __amdgpu_buffer_rsrc_t rs = __builtin_amdgcn_make_buffer_rsrc((void*)KV8, 0, 0x7fffffff, 0x00020000);
;     const int lvo = lane * 16;
;     LAS float* srow = sbuf + hd * 256;
.LBB0_1247:
	v_readlane_b32 s4, v248, 4
	v_readlane_b32 s5, v248, 5
	s_andn2_b64 vcc, exec, s[4:5]
	s_waitcnt vmcnt(0) lgkmcnt(0)
	s_barrier
	s_cbranch_vccnz .LBB0_1377
	s_mul_i32 s0, s81, 0x800
	s_and_b32 s5, s2, 7
	s_lshr_b32 s8, s2, 3
	s_lshl_b32 s8, s8, 3
	s_add_i32 s80, s8, s81
	s_lshl_b32 s8, s5, 22
	s_add_u32 s16, s60, 0x1b800000
	s_addc_u32 s17, s61, 0
	s_add_u32 s16, s16, s8
	s_addc_u32 s17, s17, 0
	s_and_b32 s17, s17, 0xffff
	s_mov_b32 s18, 0x400000
	s_mov_b32 s19, 0x20000
	s_mov_b32 s26, 0
	s_movk_i32 s27, 0x80
	s_mov_b32 s28, 0x3fb8aa3b
	v_and_b32_e32 v132, 7, v144
	v_lshlrev_b32_e32 v138, 4, v132
	v_lshrrev_b32_e32 v145, 3, v144
	v_lshl_add_u32 v139, v145, 7, s0
	v_lshl_add_u32 v148, v132, 7, s0
	v_lshl_add_u32 v148, v145, 2, v148
	v_xor_b32_e32 v140, 16, v144
	v_lshlrev_b32_e32 v140, 2, v140
	v_xor_b32_e32 v141, 32, v144
	v_lshlrev_b32_e32 v141, 2, v141
	v_mov_b32_e32 v142, 0xff800000
	v_lshlrev_b32_e32 v147, 2, v144
	s_lshl_b32 s8, s5, 8
	v_lshl_add_u32 v146, v132, 5, s8
	s_min_i32 s8, s80, 0xff
	s_add_i32 s8, s8, 1
	s_lshl_b32 s10, s80, 10
	s_add_u32 s10, s1, s10
	s_addc_u32 s11, s73, 0
	v_mov_b32_e32 v240, 0
	v_add_u32_e32 v133, 0, v144
	v_cmp_gt_i32_e32 vcc, s8, v133
	s_and_saveexec_b64 s[12:13], vcc
	global_load_dword v240, v147, s[10:11] offset:0
	s_mov_b64 exec, s[12:13]
	v_mov_b32_e32 v241, 0
	v_add_u32_e32 v133, 64, v144
	v_cmp_gt_i32_e32 vcc, s8, v133
	s_and_saveexec_b64 s[12:13], vcc
	global_load_dword v241, v147, s[10:11] offset:256
	s_mov_b64 exec, s[12:13]
	v_mov_b32_e32 v242, 0
	v_add_u32_e32 v133, 128, v144
	v_cmp_gt_i32_e32 vcc, s8, v133
	s_and_saveexec_b64 s[12:13], vcc
	global_load_dword v242, v147, s[10:11] offset:512
	s_mov_b64 exec, s[12:13]
	v_mov_b32_e32 v243, 0
	v_add_u32_e32 v133, 192, v144
	v_cmp_gt_i32_e32 vcc, s8, v133
	s_and_saveexec_b64 s[12:13], vcc
	global_load_dword v243, v147, s[10:11] offset:768
	s_mov_b64 exec, s[12:13]
	s_mul_i32 s10, s80, 0x2a00
	s_mul_hi_i32 s11, s80, 0x2a00
	s_add_u32 s10, s42, s10
	s_addc_u32 s11, s43, s11
	global_load_dwordx4 v[244:247], v146, s[10:11] offset:2048
	global_load_dwordx4 v[230:233], v146, s[10:11] offset:2064
	s_waitcnt vmcnt(0)
	ds_write_b32 v148, v240 offset:0
	ds_write_b32 v148, v241 offset:32
	ds_write_b32 v148, v242 offset:64
	ds_write_b32 v148, v243 offset:96
	s_waitcnt lgkmcnt(0)
	ds_read_b128 v[150:153], v139 offset:0
	ds_read_b128 v[154:157], v139 offset:16
	ds_read_b128 v[158:161], v139 offset:32
	ds_read_b128 v[162:165], v139 offset:48
	ds_read_b128 v[166:169], v139 offset:64
	ds_read_b128 v[170:173], v139 offset:80
	ds_read_b128 v[174:177], v139 offset:96
	ds_read_b128 v[178:181], v139 offset:112
	s_waitcnt lgkmcnt(0)
	v_lshl_add_u32 v150, v150, 8, v138
	v_lshl_add_u32 v151, v151, 8, v138
	v_lshl_add_u32 v152, v152, 8, v138
	v_lshl_add_u32 v153, v153, 8, v138
	v_lshl_add_u32 v154, v154, 8, v138
	v_lshl_add_u32 v155, v155, 8, v138
	v_lshl_add_u32 v156, v156, 8, v138
	v_lshl_add_u32 v157, v157, 8, v138
	v_lshl_add_u32 v158, v158, 8, v138
	v_lshl_add_u32 v159, v159, 8, v138
	v_lshl_add_u32 v160, v160, 8, v138
	v_lshl_add_u32 v161, v161, 8, v138
	v_lshl_add_u32 v162, v162, 8, v138
	v_lshl_add_u32 v163, v163, 8, v138
	v_lshl_add_u32 v164, v164, 8, v138
	v_lshl_add_u32 v165, v165, 8, v138
	v_lshl_add_u32 v166, v166, 8, v138
	v_lshl_add_u32 v167, v167, 8, v138
	v_lshl_add_u32 v168, v168, 8, v138
	v_lshl_add_u32 v169, v169, 8, v138
	v_lshl_add_u32 v170, v170, 8, v138
	v_lshl_add_u32 v171, v171, 8, v138
	v_lshl_add_u32 v172, v172, 8, v138
	v_lshl_add_u32 v173, v173, 8, v138
	v_lshl_add_u32 v174, v174, 8, v138
	v_lshl_add_u32 v175, v175, 8, v138
	v_lshl_add_u32 v176, v176, 8, v138
	v_lshl_add_u32 v177, v177, 8, v138
	v_lshl_add_u32 v178, v178, 8, v138
	v_lshl_add_u32 v179, v179, 8, v138
	v_lshl_add_u32 v180, v180, 8, v138
	v_lshl_add_u32 v181, v181, 8, v138
	buffer_load_dwordx4 v[0:3], v150, s[16:19], s26 offen sc0
	buffer_load_dwordx4 v[4:7], v151, s[16:19], s26 offen sc0
	buffer_load_dwordx4 v[8:11], v152, s[16:19], s26 offen sc0
	buffer_load_dwordx4 v[12:15], v153, s[16:19], s26 offen sc0
	buffer_load_dwordx4 v[16:19], v154, s[16:19], s26 offen sc0
	buffer_load_dwordx4 v[20:23], v155, s[16:19], s26 offen sc0
	buffer_load_dwordx4 v[24:27], v156, s[16:19], s26 offen sc0
	buffer_load_dwordx4 v[28:31], v157, s[16:19], s26 offen sc0
	buffer_load_dwordx4 v[32:35], v158, s[16:19], s26 offen sc0
	buffer_load_dwordx4 v[36:39], v159, s[16:19], s26 offen sc0
	buffer_load_dwordx4 v[40:43], v160, s[16:19], s26 offen sc0
	buffer_load_dwordx4 v[44:47], v161, s[16:19], s26 offen sc0
	buffer_load_dwordx4 v[48:51], v162, s[16:19], s26 offen sc0
	buffer_load_dwordx4 v[52:55], v163, s[16:19], s26 offen sc0
	buffer_load_dwordx4 v[56:59], v164, s[16:19], s26 offen sc0
	buffer_load_dwordx4 v[60:63], v165, s[16:19], s26 offen sc0
	buffer_load_dwordx4 v[64:67], v166, s[16:19], s26 offen sc0
	buffer_load_dwordx4 v[68:71], v167, s[16:19], s26 offen sc0
	buffer_load_dwordx4 v[72:75], v168, s[16:19], s26 offen sc0
	buffer_load_dwordx4 v[76:79], v169, s[16:19], s26 offen sc0
	buffer_load_dwordx4 v[80:83], v170, s[16:19], s26 offen sc0
	buffer_load_dwordx4 v[84:87], v171, s[16:19], s26 offen sc0
	buffer_load_dwordx4 v[88:91], v172, s[16:19], s26 offen sc0
	buffer_load_dwordx4 v[92:95], v173, s[16:19], s26 offen sc0
	buffer_load_dwordx4 v[96:99], v174, s[16:19], s26 offen sc0
	buffer_load_dwordx4 v[100:103], v175, s[16:19], s26 offen sc0
	buffer_load_dwordx4 v[104:107], v176, s[16:19], s26 offen sc0
	buffer_load_dwordx4 v[108:111], v177, s[16:19], s26 offen sc0
	buffer_load_dwordx4 v[112:115], v178, s[16:19], s26 offen sc0
	buffer_load_dwordx4 v[116:119], v179, s[16:19], s26 offen sc0
	buffer_load_dwordx4 v[120:123], v180, s[16:19], s26 offen sc0
	buffer_load_dwordx4 v[124:127], v181, s[16:19], s26 offen sc0
; __device__ __forceinline__ float bf_lo(unsigned v) { return __uint_as_float(v << 16); }
; __device__ __forceinline__ float bf_hi(unsigned v) { return __uint_as_float(v & 0xffff0000u); }
; __device__ __forceinline__ float red8(float v) { v += dpp_f<0xB1>(v); v += dpp_f<0x4E>(v); v += dpp_f<0x141>(v); return v; }
; __device__ __forceinline__ void kv8_qk(const u32x4 (&buf)[8], const f32x2v (&q2)[8], LAS float* srow, int b, int lane) {
;     ...
;     for (int u = 0; u < 8; ++u) {
;         const u32x4 k = buf[u];
;         f32x2v s0 = q2[0] * __builtin_amdgcn_cvt_pk_f32_fp8(k.x, false), s1 = q2[1] * __builtin_amdgcn_cvt_pk_f32_fp8(k.x, true);
;         s0 = __builtin_elementwise_fma(q2[2], __builtin_amdgcn_cvt_pk_f32_fp8(k.y, false), s0); s1 = __builtin_elementwise_fma(q2[3], __builtin_amdgcn_cvt_pk_f32_fp8(k.y, true), s1);
;         s0 = __builtin_elementwise_fma(q2[4], __builtin_amdgcn_cvt_pk_f32_fp8(k.z, false), s0); s1 = __builtin_elementwise_fma(q2[5], __builtin_amdgcn_cvt_pk_f32_fp8(k.z, true), s1);
;         s0 = __builtin_elementwise_fma(q2[6], __builtin_amdgcn_cvt_pk_f32_fp8(k.w, false), s0); s1 = __builtin_elementwise_fma(q2[7], __builtin_amdgcn_cvt_pk_f32_fp8(k.w, true), s1);
;         const f32x2v t = s0 + s1;
;         const float s = red8(t.x + t.y);
;         if ((lane & 7) == 0) srow[b * 8 + u] = s;
;     }
; __device__ __forceinline__ void attn_query8(const unsigned char* __restrict__ KV8, const bf16_t* __restrict__ Z, const int* __restrict__ SEL, bf16_t* __restrict__ YMIX, int t, LAS float* sbuf  ) {
;     ...
;     const int nsel = (t + 1 < 256) ? (t + 1) : 256, nb = (nsel + 7) >> 3;
;     int iv[4];
; #pragma unroll
;     for (int jj = 0; jj < 4; ++jj) { const int e = lane + 64 * jj; iv[jj] = (e < nsel) ? SEL[(size_t)t * 256 + e] : 0; }
;     f32x2v qf[8];
;     { const u32x4* qp = (const u32x4*)(Z + (size_t)t * ZLD + OFF_Q + lane * 16); const u32x4 a = qp[0], b = qp[1];
;       qf[0] = (f32x2v){bf_lo(a.x), bf_hi(a.x)}; qf[1] = (f32x2v){bf_lo(a.y), bf_hi(a.y)}; qf[2] = (f32x2v){bf_lo(a.z), bf_hi(a.z)}; qf[3] = (f32x2v){bf_lo(a.w), bf_hi(a.w)};
;       qf[4] = (f32x2v){bf_lo(b.x), bf_hi(b.x)}; qf[5] = (f32x2v){bf_lo(b.y), bf_hi(b.y)}; qf[6] = (f32x2v){bf_lo(b.z), bf_hi(b.z)}; qf[7] = (f32x2v){bf_lo(b.w), bf_hi(b.w)}; }
.Latt_unit:
	s_min_i32 s4, s80, 0xff
	s_add_i32 s4, s4, 1
	v_sub_u32_e32 v143, s4, v145
	s_waitcnt vmcnt(32)
	v_lshlrev_b32_e32 v182, 16, v244
	v_and_b32_e32 v183, 0xffff0000, v244
	v_lshlrev_b32_e32 v184, 16, v245
	v_and_b32_e32 v185, 0xffff0000, v245
	v_lshlrev_b32_e32 v186, 16, v246
	v_and_b32_e32 v187, 0xffff0000, v246
	v_lshlrev_b32_e32 v188, 16, v247
	v_and_b32_e32 v189, 0xffff0000, v247
	v_lshlrev_b32_e32 v190, 16, v230
	v_and_b32_e32 v191, 0xffff0000, v230
	v_lshlrev_b32_e32 v192, 16, v231
	v_and_b32_e32 v193, 0xffff0000, v231
	v_lshlrev_b32_e32 v194, 16, v232
	v_and_b32_e32 v195, 0xffff0000, v232
	v_lshlrev_b32_e32 v196, 16, v233
	v_and_b32_e32 v197, 0xffff0000, v233
	s_add_i32 s6, s80, 0x100
	s_min_i32 s6, s6, 0x3fff
	s_min_i32 s8, s6, 0xff
	s_add_i32 s8, s8, 1
	s_lshl_b32 s10, s6, 10
	s_add_u32 s10, s1, s10
	s_addc_u32 s11, s73, 0
	v_mov_b32_e32 v240, 0
	v_add_u32_e32 v133, 0, v144
	v_cmp_gt_i32_e32 vcc, s8, v133
	s_and_saveexec_b64 s[12:13], vcc
	global_load_dword v240, v147, s[10:11] offset:0
	s_mov_b64 exec, s[12:13]
	v_mov_b32_e32 v241, 0
	v_add_u32_e32 v133, 64, v144
	v_cmp_gt_i32_e32 vcc, s8, v133
	s_and_saveexec_b64 s[12:13], vcc
	global_load_dword v241, v147, s[10:11] offset:256
	s_mov_b64 exec, s[12:13]
	v_mov_b32_e32 v242, 0
	v_add_u32_e32 v133, 128, v144
	v_cmp_gt_i32_e32 vcc, s8, v133
	s_and_saveexec_b64 s[12:13], vcc
	global_load_dword v242, v147, s[10:11] offset:512
	s_mov_b64 exec, s[12:13]
	v_mov_b32_e32 v243, 0
	v_add_u32_e32 v133, 192, v144
	v_cmp_gt_i32_e32 vcc, s8, v133
	s_and_saveexec_b64 s[12:13], vcc
	global_load_dword v243, v147, s[10:11] offset:768
	s_mov_b64 exec, s[12:13]
	s_mul_i32 s10, s6, 0x2a00
	s_mul_hi_i32 s11, s6, 0x2a00
	s_add_u32 s10, s42, s10
	s_addc_u32 s11, s43, s11
	global_load_dwordx4 v[244:247], v146, s[10:11] offset:2048
	global_load_dwordx4 v[230:233], v146, s[10:11] offset:2064
	s_waitcnt vmcnt(37)
	v_cvt_pk_f32_fp8_e32 v[214:215], v0
	v_cvt_pk_f32_fp8_sdwa v[216:217], v0 src0_sel:WORD_1
	v_cvt_pk_f32_fp8_e32 v[218:219], v1
	s_nop 0
	v_cvt_pk_f32_fp8_sdwa v[220:221], v1 src0_sel:WORD_1
	v_cvt_pk_f32_fp8_e32 v[222:223], v2
	v_cvt_pk_f32_fp8_sdwa v[224:225], v2 src0_sel:WORD_1
	v_cvt_pk_f32_fp8_e32 v[226:227], v3
	s_nop 0
	v_cvt_pk_f32_fp8_sdwa v[228:229], v3 src0_sel:WORD_1
	v_pk_mul_f32 v[128:129], v[214:215], v[182:183]
	v_pk_mul_f32 v[130:131], v[216:217], v[184:185]
	v_pk_fma_f32 v[128:129], v[186:187], v[218:219], v[128:129]
	v_pk_fma_f32 v[130:131], v[188:189], v[220:221], v[130:131]
	v_pk_fma_f32 v[128:129], v[190:191], v[222:223], v[128:129]
	v_pk_fma_f32 v[130:131], v[192:193], v[224:225], v[130:131]
	v_pk_fma_f32 v[128:129], v[194:195], v[226:227], v[128:129]
	v_pk_fma_f32 v[130:131], v[196:197], v[228:229], v[130:131]
	buffer_load_dwordx4 v[0:3], v150, s[16:19], s27 offen sc0
	v_pk_add_f32 v[128:129], v[128:129], v[130:131]
	s_nop 0
	v_add_f32_e32 v132, v128, v129
	s_waitcnt vmcnt(37)
	v_cvt_pk_f32_fp8_e32 v[214:215], v4
	v_cvt_pk_f32_fp8_sdwa v[216:217], v4 src0_sel:WORD_1
	v_cvt_pk_f32_fp8_e32 v[218:219], v5
	v_add_f32_dpp v132, v132, v132 quad_perm:[1,0,3,2] row_mask:0xf bank_mask:0xf
	v_cvt_pk_f32_fp8_sdwa v[220:221], v5 src0_sel:WORD_1
	v_cvt_pk_f32_fp8_e32 v[222:223], v6
	v_cvt_pk_f32_fp8_sdwa v[224:225], v6 src0_sel:WORD_1
	v_cvt_pk_f32_fp8_e32 v[226:227], v7
	v_add_f32_dpp v132, v132, v132 quad_perm:[2,3,0,1] row_mask:0xf bank_mask:0xf
	v_cvt_pk_f32_fp8_sdwa v[228:229], v7 src0_sel:WORD_1
	v_pk_mul_f32 v[128:129], v[214:215], v[182:183]
	v_pk_mul_f32 v[130:131], v[216:217], v[184:185]
	v_pk_fma_f32 v[128:129], v[186:187], v[218:219], v[128:129]
	v_pk_fma_f32 v[130:131], v[188:189], v[220:221], v[130:131]
	v_pk_fma_f32 v[128:129], v[190:191], v[222:223], v[128:129]
	v_pk_fma_f32 v[130:131], v[192:193], v[224:225], v[130:131]
	v_pk_fma_f32 v[128:129], v[194:195], v[226:227], v[128:129]
	v_pk_fma_f32 v[130:131], v[196:197], v[228:229], v[130:131]
	buffer_load_dwordx4 v[4:7], v151, s[16:19], s27 offen sc0
	v_pk_add_f32 v[128:129], v[128:129], v[130:131]
	v_add_f32_dpp v150, v132, v132 row_half_mirror row_mask:0xf bank_mask:0xf
	v_add_f32_e32 v133, v128, v129
	s_waitcnt vmcnt(37)
	v_cvt_pk_f32_fp8_e32 v[214:215], v8
	v_cvt_pk_f32_fp8_sdwa v[216:217], v8 src0_sel:WORD_1
	v_cvt_pk_f32_fp8_e32 v[218:219], v9
	v_add_f32_dpp v133, v133, v133 quad_perm:[1,0,3,2] row_mask:0xf bank_mask:0xf
	v_cvt_pk_f32_fp8_sdwa v[220:221], v9 src0_sel:WORD_1
	v_cvt_pk_f32_fp8_e32 v[222:223], v10
	v_cvt_pk_f32_fp8_sdwa v[224:225], v10 src0_sel:WORD_1
	v_cvt_pk_f32_fp8_e32 v[226:227], v11
	v_add_f32_dpp v133, v133, v133 quad_perm:[2,3,0,1] row_mask:0xf bank_mask:0xf
	v_cvt_pk_f32_fp8_sdwa v[228:229], v11 src0_sel:WORD_1
	v_pk_mul_f32 v[128:129], v[214:215], v[182:183]
	v_pk_mul_f32 v[130:131], v[216:217], v[184:185]
	v_pk_fma_f32 v[128:129], v[186:187], v[218:219], v[128:129]
	v_pk_fma_f32 v[130:131], v[188:189], v[220:221], v[130:131]
	v_pk_fma_f32 v[128:129], v[190:191], v[222:223], v[128:129]
	v_pk_fma_f32 v[130:131], v[192:193], v[224:225], v[130:131]
	v_pk_fma_f32 v[128:129], v[194:195], v[226:227], v[128:129]
	v_pk_fma_f32 v[130:131], v[196:197], v[228:229], v[130:131]
	buffer_load_dwordx4 v[8:11], v152, s[16:19], s27 offen sc0
	v_pk_add_f32 v[128:129], v[128:129], v[130:131]
	v_add_f32_dpp v151, v133, v133 row_half_mirror row_mask:0xf bank_mask:0xf
	v_add_f32_e32 v132, v128, v129
	s_waitcnt vmcnt(37)
; __device__ __forceinline__ float red8(float v) { v += dpp_f<0xB1>(v); v += dpp_f<0x4E>(v); v += dpp_f<0x141>(v); return v; }
; __device__ __forceinline__ void kv8_qk(const u32x4 (&buf)[8], const f32x2v (&q2)[8], LAS float* srow, int b, int lane) {
;     ...
;     for (int u = 0; u < 8; ++u) {
;         const u32x4 k = buf[u];
;         f32x2v s0 = q2[0] * __builtin_amdgcn_cvt_pk_f32_fp8(k.x, false), s1 = q2[1] * __builtin_amdgcn_cvt_pk_f32_fp8(k.x, true);
;         s0 = __builtin_elementwise_fma(q2[2], __builtin_amdgcn_cvt_pk_f32_fp8(k.y, false), s0); s1 = __builtin_elementwise_fma(q2[3], __builtin_amdgcn_cvt_pk_f32_fp8(k.y, true), s1);
;         s0 = __builtin_elementwise_fma(q2[4], __builtin_amdgcn_cvt_pk_f32_fp8(k.z, false), s0); s1 = __builtin_elementwise_fma(q2[5], __builtin_amdgcn_cvt_pk_f32_fp8(k.z, true), s1);
;         s0 = __builtin_elementwise_fma(q2[6], __builtin_amdgcn_cvt_pk_f32_fp8(k.w, false), s0); s1 = __builtin_elementwise_fma(q2[7], __builtin_amdgcn_cvt_pk_f32_fp8(k.w, true), s1);
;         const f32x2v t = s0 + s1;
;         const float s = red8(t.x + t.y);
;         if ((lane & 7) == 0) srow[b * 8 + u] = s;
;     }
	v_cvt_pk_f32_fp8_e32 v[214:215], v12
	v_cvt_pk_f32_fp8_sdwa v[216:217], v12 src0_sel:WORD_1
	v_cvt_pk_f32_fp8_e32 v[218:219], v13
	v_add_f32_dpp v132, v132, v132 quad_perm:[1,0,3,2] row_mask:0xf bank_mask:0xf
	v_cvt_pk_f32_fp8_sdwa v[220:221], v13 src0_sel:WORD_1
	v_cvt_pk_f32_fp8_e32 v[222:223], v14
	v_cvt_pk_f32_fp8_sdwa v[224:225], v14 src0_sel:WORD_1
	v_cvt_pk_f32_fp8_e32 v[226:227], v15
	v_add_f32_dpp v132, v132, v132 quad_perm:[2,3,0,1] row_mask:0xf bank_mask:0xf
	v_cvt_pk_f32_fp8_sdwa v[228:229], v15 src0_sel:WORD_1
	v_pk_mul_f32 v[128:129], v[214:215], v[182:183]
	v_pk_mul_f32 v[130:131], v[216:217], v[184:185]
	v_pk_fma_f32 v[128:129], v[186:187], v[218:219], v[128:129]
	v_pk_fma_f32 v[130:131], v[188:189], v[220:221], v[130:131]
	v_pk_fma_f32 v[128:129], v[190:191], v[222:223], v[128:129]
	v_pk_fma_f32 v[130:131], v[192:193], v[224:225], v[130:131]
	v_pk_fma_f32 v[128:129], v[194:195], v[226:227], v[128:129]
	v_pk_fma_f32 v[130:131], v[196:197], v[228:229], v[130:131]
	buffer_load_dwordx4 v[12:15], v153, s[16:19], s27 offen sc0
	v_pk_add_f32 v[128:129], v[128:129], v[130:131]
	v_add_f32_dpp v152, v132, v132 row_half_mirror row_mask:0xf bank_mask:0xf
	v_add_f32_e32 v133, v128, v129
	s_waitcnt vmcnt(37)
	v_cvt_pk_f32_fp8_e32 v[214:215], v16
	v_cvt_pk_f32_fp8_sdwa v[216:217], v16 src0_sel:WORD_1
	v_cvt_pk_f32_fp8_e32 v[218:219], v17
	v_add_f32_dpp v133, v133, v133 quad_perm:[1,0,3,2] row_mask:0xf bank_mask:0xf
	v_cvt_pk_f32_fp8_sdwa v[220:221], v17 src0_sel:WORD_1
	v_cvt_pk_f32_fp8_e32 v[222:223], v18
	v_cvt_pk_f32_fp8_sdwa v[224:225], v18 src0_sel:WORD_1
	v_cvt_pk_f32_fp8_e32 v[226:227], v19
	v_add_f32_dpp v133, v133, v133 quad_perm:[2,3,0,1] row_mask:0xf bank_mask:0xf
	v_cvt_pk_f32_fp8_sdwa v[228:229], v19 src0_sel:WORD_1
	v_pk_mul_f32 v[128:129], v[214:215], v[182:183]
	v_pk_mul_f32 v[130:131], v[216:217], v[184:185]
	v_pk_fma_f32 v[128:129], v[186:187], v[218:219], v[128:129]
	v_pk_fma_f32 v[130:131], v[188:189], v[220:221], v[130:131]
	v_pk_fma_f32 v[128:129], v[190:191], v[222:223], v[128:129]
	v_pk_fma_f32 v[130:131], v[192:193], v[224:225], v[130:131]
	v_pk_fma_f32 v[128:129], v[194:195], v[226:227], v[128:129]
	v_pk_fma_f32 v[130:131], v[196:197], v[228:229], v[130:131]
	buffer_load_dwordx4 v[16:19], v154, s[16:19], s27 offen sc0
	v_pk_add_f32 v[128:129], v[128:129], v[130:131]
	v_add_f32_dpp v153, v133, v133 row_half_mirror row_mask:0xf bank_mask:0xf
	v_add_f32_e32 v132, v128, v129
	s_waitcnt vmcnt(37)
	v_cvt_pk_f32_fp8_e32 v[214:215], v20
	v_cvt_pk_f32_fp8_sdwa v[216:217], v20 src0_sel:WORD_1
	v_cvt_pk_f32_fp8_e32 v[218:219], v21
	v_add_f32_dpp v132, v132, v132 quad_perm:[1,0,3,2] row_mask:0xf bank_mask:0xf
	v_cvt_pk_f32_fp8_sdwa v[220:221], v21 src0_sel:WORD_1
	v_cvt_pk_f32_fp8_e32 v[222:223], v22
	v_cvt_pk_f32_fp8_sdwa v[224:225], v22 src0_sel:WORD_1
	v_cvt_pk_f32_fp8_e32 v[226:227], v23
	v_add_f32_dpp v132, v132, v132 quad_perm:[2,3,0,1] row_mask:0xf bank_mask:0xf
	v_cvt_pk_f32_fp8_sdwa v[228:229], v23 src0_sel:WORD_1
	v_pk_mul_f32 v[128:129], v[214:215], v[182:183]
	v_pk_mul_f32 v[130:131], v[216:217], v[184:185]
	v_pk_fma_f32 v[128:129], v[186:187], v[218:219], v[128:129]
	v_pk_fma_f32 v[130:131], v[188:189], v[220:221], v[130:131]
	v_pk_fma_f32 v[128:129], v[190:191], v[222:223], v[128:129]
	v_pk_fma_f32 v[130:131], v[192:193], v[224:225], v[130:131]
	v_pk_fma_f32 v[128:129], v[194:195], v[226:227], v[128:129]
	v_pk_fma_f32 v[130:131], v[196:197], v[228:229], v[130:131]
	buffer_load_dwordx4 v[20:23], v155, s[16:19], s27 offen sc0
	v_pk_add_f32 v[128:129], v[128:129], v[130:131]
	v_add_f32_dpp v154, v132, v132 row_half_mirror row_mask:0xf bank_mask:0xf
	v_add_f32_e32 v133, v128, v129
	s_waitcnt vmcnt(37)
	v_cvt_pk_f32_fp8_e32 v[214:215], v24
	v_cvt_pk_f32_fp8_sdwa v[216:217], v24 src0_sel:WORD_1
	v_cvt_pk_f32_fp8_e32 v[218:219], v25
	v_add_f32_dpp v133, v133, v133 quad_perm:[1,0,3,2] row_mask:0xf bank_mask:0xf
	v_cvt_pk_f32_fp8_sdwa v[220:221], v25 src0_sel:WORD_1
	v_cvt_pk_f32_fp8_e32 v[222:223], v26
	v_cvt_pk_f32_fp8_sdwa v[224:225], v26 src0_sel:WORD_1
	v_cvt_pk_f32_fp8_e32 v[226:227], v27
	v_add_f32_dpp v133, v133, v133 quad_perm:[2,3,0,1] row_mask:0xf bank_mask:0xf
	v_cvt_pk_f32_fp8_sdwa v[228:229], v27 src0_sel:WORD_1
	v_pk_mul_f32 v[128:129], v[214:215], v[182:183]
	v_pk_mul_f32 v[130:131], v[216:217], v[184:185]
	v_pk_fma_f32 v[128:129], v[186:187], v[218:219], v[128:129]
	v_pk_fma_f32 v[130:131], v[188:189], v[220:221], v[130:131]
	v_pk_fma_f32 v[128:129], v[190:191], v[222:223], v[128:129]
	v_pk_fma_f32 v[130:131], v[192:193], v[224:225], v[130:131]
	v_pk_fma_f32 v[128:129], v[194:195], v[226:227], v[128:129]
	v_pk_fma_f32 v[130:131], v[196:197], v[228:229], v[130:131]
	buffer_load_dwordx4 v[24:27], v156, s[16:19], s27 offen sc0
	v_pk_add_f32 v[128:129], v[128:129], v[130:131]
	v_add_f32_dpp v155, v133, v133 row_half_mirror row_mask:0xf bank_mask:0xf
	v_add_f32_e32 v132, v128, v129
	s_waitcnt vmcnt(37)
	v_cvt_pk_f32_fp8_e32 v[214:215], v28
	v_cvt_pk_f32_fp8_sdwa v[216:217], v28 src0_sel:WORD_1
	v_cvt_pk_f32_fp8_e32 v[218:219], v29
	v_add_f32_dpp v132, v132, v132 quad_perm:[1,0,3,2] row_mask:0xf bank_mask:0xf
	v_cvt_pk_f32_fp8_sdwa v[220:221], v29 src0_sel:WORD_1
	v_cvt_pk_f32_fp8_e32 v[222:223], v30
	v_cvt_pk_f32_fp8_sdwa v[224:225], v30 src0_sel:WORD_1
	v_cvt_pk_f32_fp8_e32 v[226:227], v31
	v_add_f32_dpp v132, v132, v132 quad_perm:[2,3,0,1] row_mask:0xf bank_mask:0xf
	v_cvt_pk_f32_fp8_sdwa v[228:229], v31 src0_sel:WORD_1
	v_pk_mul_f32 v[128:129], v[214:215], v[182:183]
	v_pk_mul_f32 v[130:131], v[216:217], v[184:185]
	v_pk_fma_f32 v[128:129], v[186:187], v[218:219], v[128:129]
	v_pk_fma_f32 v[130:131], v[188:189], v[220:221], v[130:131]
	v_pk_fma_f32 v[128:129], v[190:191], v[222:223], v[128:129]
	v_pk_fma_f32 v[130:131], v[192:193], v[224:225], v[130:131]
	v_pk_fma_f32 v[128:129], v[194:195], v[226:227], v[128:129]
	v_pk_fma_f32 v[130:131], v[196:197], v[228:229], v[130:131]
	buffer_load_dwordx4 v[28:31], v157, s[16:19], s27 offen sc0
	v_pk_add_f32 v[128:129], v[128:129], v[130:131]
	v_add_f32_dpp v156, v132, v132 row_half_mirror row_mask:0xf bank_mask:0xf
	v_add_f32_e32 v133, v128, v129
	s_waitcnt vmcnt(37)
; __device__ __forceinline__ float red8(float v) { v += dpp_f<0xB1>(v); v += dpp_f<0x4E>(v); v += dpp_f<0x141>(v); return v; }
; __device__ __forceinline__ void kv8_qk(const u32x4 (&buf)[8], const f32x2v (&q2)[8], LAS float* srow, int b, int lane) {
;     ...
;     for (int u = 0; u < 8; ++u) {
;         const u32x4 k = buf[u];
;         f32x2v s0 = q2[0] * __builtin_amdgcn_cvt_pk_f32_fp8(k.x, false), s1 = q2[1] * __builtin_amdgcn_cvt_pk_f32_fp8(k.x, true);
;         s0 = __builtin_elementwise_fma(q2[2], __builtin_amdgcn_cvt_pk_f32_fp8(k.y, false), s0); s1 = __builtin_elementwise_fma(q2[3], __builtin_amdgcn_cvt_pk_f32_fp8(k.y, true), s1);
;         s0 = __builtin_elementwise_fma(q2[4], __builtin_amdgcn_cvt_pk_f32_fp8(k.z, false), s0); s1 = __builtin_elementwise_fma(q2[5], __builtin_amdgcn_cvt_pk_f32_fp8(k.z, true), s1);
;         s0 = __builtin_elementwise_fma(q2[6], __builtin_amdgcn_cvt_pk_f32_fp8(k.w, false), s0); s1 = __builtin_elementwise_fma(q2[7], __builtin_amdgcn_cvt_pk_f32_fp8(k.w, true), s1);
;         const f32x2v t = s0 + s1;
;         const float s = red8(t.x + t.y);
;         if ((lane & 7) == 0) srow[b * 8 + u] = s;
;     }
	v_cvt_pk_f32_fp8_e32 v[214:215], v32
	v_cvt_pk_f32_fp8_sdwa v[216:217], v32 src0_sel:WORD_1
	v_cvt_pk_f32_fp8_e32 v[218:219], v33
	v_add_f32_dpp v133, v133, v133 quad_perm:[1,0,3,2] row_mask:0xf bank_mask:0xf
	v_cvt_pk_f32_fp8_sdwa v[220:221], v33 src0_sel:WORD_1
	v_cvt_pk_f32_fp8_e32 v[222:223], v34
	v_cvt_pk_f32_fp8_sdwa v[224:225], v34 src0_sel:WORD_1
	v_cvt_pk_f32_fp8_e32 v[226:227], v35
	v_add_f32_dpp v133, v133, v133 quad_perm:[2,3,0,1] row_mask:0xf bank_mask:0xf
	v_cvt_pk_f32_fp8_sdwa v[228:229], v35 src0_sel:WORD_1
	v_pk_mul_f32 v[128:129], v[214:215], v[182:183]
	v_pk_mul_f32 v[130:131], v[216:217], v[184:185]
	v_pk_fma_f32 v[128:129], v[186:187], v[218:219], v[128:129]
	v_pk_fma_f32 v[130:131], v[188:189], v[220:221], v[130:131]
	v_pk_fma_f32 v[128:129], v[190:191], v[222:223], v[128:129]
	v_pk_fma_f32 v[130:131], v[192:193], v[224:225], v[130:131]
	v_pk_fma_f32 v[128:129], v[194:195], v[226:227], v[128:129]
	v_pk_fma_f32 v[130:131], v[196:197], v[228:229], v[130:131]
	buffer_load_dwordx4 v[32:35], v158, s[16:19], s27 offen sc0
	v_pk_add_f32 v[128:129], v[128:129], v[130:131]
	v_add_f32_dpp v157, v133, v133 row_half_mirror row_mask:0xf bank_mask:0xf
	v_add_f32_e32 v132, v128, v129
	s_waitcnt vmcnt(37)
	v_cvt_pk_f32_fp8_e32 v[214:215], v36
	v_cvt_pk_f32_fp8_sdwa v[216:217], v36 src0_sel:WORD_1
	v_cvt_pk_f32_fp8_e32 v[218:219], v37
	v_add_f32_dpp v132, v132, v132 quad_perm:[1,0,3,2] row_mask:0xf bank_mask:0xf
	v_cvt_pk_f32_fp8_sdwa v[220:221], v37 src0_sel:WORD_1
	v_cvt_pk_f32_fp8_e32 v[222:223], v38
	v_cvt_pk_f32_fp8_sdwa v[224:225], v38 src0_sel:WORD_1
	v_cvt_pk_f32_fp8_e32 v[226:227], v39
	v_add_f32_dpp v132, v132, v132 quad_perm:[2,3,0,1] row_mask:0xf bank_mask:0xf
	v_cvt_pk_f32_fp8_sdwa v[228:229], v39 src0_sel:WORD_1
	v_pk_mul_f32 v[128:129], v[214:215], v[182:183]
	v_pk_mul_f32 v[130:131], v[216:217], v[184:185]
	v_pk_fma_f32 v[128:129], v[186:187], v[218:219], v[128:129]
	v_pk_fma_f32 v[130:131], v[188:189], v[220:221], v[130:131]
	v_pk_fma_f32 v[128:129], v[190:191], v[222:223], v[128:129]
	v_pk_fma_f32 v[130:131], v[192:193], v[224:225], v[130:131]
	v_pk_fma_f32 v[128:129], v[194:195], v[226:227], v[128:129]
	v_pk_fma_f32 v[130:131], v[196:197], v[228:229], v[130:131]
	buffer_load_dwordx4 v[36:39], v159, s[16:19], s27 offen sc0
	v_pk_add_f32 v[128:129], v[128:129], v[130:131]
	v_add_f32_dpp v158, v132, v132 row_half_mirror row_mask:0xf bank_mask:0xf
	v_add_f32_e32 v133, v128, v129
	s_waitcnt vmcnt(37)
	v_cvt_pk_f32_fp8_e32 v[214:215], v40
	v_cvt_pk_f32_fp8_sdwa v[216:217], v40 src0_sel:WORD_1
	v_cvt_pk_f32_fp8_e32 v[218:219], v41
	v_add_f32_dpp v133, v133, v133 quad_perm:[1,0,3,2] row_mask:0xf bank_mask:0xf
	v_cvt_pk_f32_fp8_sdwa v[220:221], v41 src0_sel:WORD_1
	v_cvt_pk_f32_fp8_e32 v[222:223], v42
	v_cvt_pk_f32_fp8_sdwa v[224:225], v42 src0_sel:WORD_1
	v_cvt_pk_f32_fp8_e32 v[226:227], v43
	v_add_f32_dpp v133, v133, v133 quad_perm:[2,3,0,1] row_mask:0xf bank_mask:0xf
	v_cvt_pk_f32_fp8_sdwa v[228:229], v43 src0_sel:WORD_1
	v_pk_mul_f32 v[128:129], v[214:215], v[182:183]
	v_pk_mul_f32 v[130:131], v[216:217], v[184:185]
	v_pk_fma_f32 v[128:129], v[186:187], v[218:219], v[128:129]
	v_pk_fma_f32 v[130:131], v[188:189], v[220:221], v[130:131]
	v_pk_fma_f32 v[128:129], v[190:191], v[222:223], v[128:129]
	v_pk_fma_f32 v[130:131], v[192:193], v[224:225], v[130:131]
	v_pk_fma_f32 v[128:129], v[194:195], v[226:227], v[128:129]
	v_pk_fma_f32 v[130:131], v[196:197], v[228:229], v[130:131]
	buffer_load_dwordx4 v[40:43], v160, s[16:19], s27 offen sc0
	v_pk_add_f32 v[128:129], v[128:129], v[130:131]
	v_add_f32_dpp v159, v133, v133 row_half_mirror row_mask:0xf bank_mask:0xf
	v_add_f32_e32 v132, v128, v129
	s_waitcnt vmcnt(37)
	v_cvt_pk_f32_fp8_e32 v[214:215], v44
	v_cvt_pk_f32_fp8_sdwa v[216:217], v44 src0_sel:WORD_1
	v_cvt_pk_f32_fp8_e32 v[218:219], v45
	v_add_f32_dpp v132, v132, v132 quad_perm:[1,0,3,2] row_mask:0xf bank_mask:0xf
	v_cvt_pk_f32_fp8_sdwa v[220:221], v45 src0_sel:WORD_1
	v_cvt_pk_f32_fp8_e32 v[222:223], v46
	v_cvt_pk_f32_fp8_sdwa v[224:225], v46 src0_sel:WORD_1
	v_cvt_pk_f32_fp8_e32 v[226:227], v47
	v_add_f32_dpp v132, v132, v132 quad_perm:[2,3,0,1] row_mask:0xf bank_mask:0xf
	v_cvt_pk_f32_fp8_sdwa v[228:229], v47 src0_sel:WORD_1
	v_pk_mul_f32 v[128:129], v[214:215], v[182:183]
	v_pk_mul_f32 v[130:131], v[216:217], v[184:185]
	v_pk_fma_f32 v[128:129], v[186:187], v[218:219], v[128:129]
	v_pk_fma_f32 v[130:131], v[188:189], v[220:221], v[130:131]
	v_pk_fma_f32 v[128:129], v[190:191], v[222:223], v[128:129]
	v_pk_fma_f32 v[130:131], v[192:193], v[224:225], v[130:131]
	v_pk_fma_f32 v[128:129], v[194:195], v[226:227], v[128:129]
	v_pk_fma_f32 v[130:131], v[196:197], v[228:229], v[130:131]
	buffer_load_dwordx4 v[44:47], v161, s[16:19], s27 offen sc0
	v_pk_add_f32 v[128:129], v[128:129], v[130:131]
	v_add_f32_dpp v160, v132, v132 row_half_mirror row_mask:0xf bank_mask:0xf
	v_add_f32_e32 v133, v128, v129
	s_waitcnt vmcnt(37)
	v_cvt_pk_f32_fp8_e32 v[214:215], v48
	v_cvt_pk_f32_fp8_sdwa v[216:217], v48 src0_sel:WORD_1
	v_cvt_pk_f32_fp8_e32 v[218:219], v49
	v_add_f32_dpp v133, v133, v133 quad_perm:[1,0,3,2] row_mask:0xf bank_mask:0xf
	v_cvt_pk_f32_fp8_sdwa v[220:221], v49 src0_sel:WORD_1
	v_cvt_pk_f32_fp8_e32 v[222:223], v50
	v_cvt_pk_f32_fp8_sdwa v[224:225], v50 src0_sel:WORD_1
	v_cvt_pk_f32_fp8_e32 v[226:227], v51
	v_add_f32_dpp v133, v133, v133 quad_perm:[2,3,0,1] row_mask:0xf bank_mask:0xf
	v_cvt_pk_f32_fp8_sdwa v[228:229], v51 src0_sel:WORD_1
	v_pk_mul_f32 v[128:129], v[214:215], v[182:183]
	v_pk_mul_f32 v[130:131], v[216:217], v[184:185]
	v_pk_fma_f32 v[128:129], v[186:187], v[218:219], v[128:129]
	v_pk_fma_f32 v[130:131], v[188:189], v[220:221], v[130:131]
	v_pk_fma_f32 v[128:129], v[190:191], v[222:223], v[128:129]
	v_pk_fma_f32 v[130:131], v[192:193], v[224:225], v[130:131]
	v_pk_fma_f32 v[128:129], v[194:195], v[226:227], v[128:129]
	v_pk_fma_f32 v[130:131], v[196:197], v[228:229], v[130:131]
	buffer_load_dwordx4 v[48:51], v162, s[16:19], s27 offen sc0
	v_pk_add_f32 v[128:129], v[128:129], v[130:131]
	v_add_f32_dpp v161, v133, v133 row_half_mirror row_mask:0xf bank_mask:0xf
	v_add_f32_e32 v132, v128, v129
	s_waitcnt vmcnt(37)
; __device__ __forceinline__ float red8(float v) { v += dpp_f<0xB1>(v); v += dpp_f<0x4E>(v); v += dpp_f<0x141>(v); return v; }
; __device__ __forceinline__ void kv8_qk(const u32x4 (&buf)[8], const f32x2v (&q2)[8], LAS float* srow, int b, int lane) {
;     ...
;     for (int u = 0; u < 8; ++u) {
;         const u32x4 k = buf[u];
;         f32x2v s0 = q2[0] * __builtin_amdgcn_cvt_pk_f32_fp8(k.x, false), s1 = q2[1] * __builtin_amdgcn_cvt_pk_f32_fp8(k.x, true);
;         s0 = __builtin_elementwise_fma(q2[2], __builtin_amdgcn_cvt_pk_f32_fp8(k.y, false), s0); s1 = __builtin_elementwise_fma(q2[3], __builtin_amdgcn_cvt_pk_f32_fp8(k.y, true), s1);
;         s0 = __builtin_elementwise_fma(q2[4], __builtin_amdgcn_cvt_pk_f32_fp8(k.z, false), s0); s1 = __builtin_elementwise_fma(q2[5], __builtin_amdgcn_cvt_pk_f32_fp8(k.z, true), s1);
;         s0 = __builtin_elementwise_fma(q2[6], __builtin_amdgcn_cvt_pk_f32_fp8(k.w, false), s0); s1 = __builtin_elementwise_fma(q2[7], __builtin_amdgcn_cvt_pk_f32_fp8(k.w, true), s1);
;         const f32x2v t = s0 + s1;
;         const float s = red8(t.x + t.y);
;         if ((lane & 7) == 0) srow[b * 8 + u] = s;
;     }
	v_cvt_pk_f32_fp8_e32 v[214:215], v52
	v_cvt_pk_f32_fp8_sdwa v[216:217], v52 src0_sel:WORD_1
	v_cvt_pk_f32_fp8_e32 v[218:219], v53
	v_add_f32_dpp v132, v132, v132 quad_perm:[1,0,3,2] row_mask:0xf bank_mask:0xf
	v_cvt_pk_f32_fp8_sdwa v[220:221], v53 src0_sel:WORD_1
	v_cvt_pk_f32_fp8_e32 v[222:223], v54
	v_cvt_pk_f32_fp8_sdwa v[224:225], v54 src0_sel:WORD_1
	v_cvt_pk_f32_fp8_e32 v[226:227], v55
	v_add_f32_dpp v132, v132, v132 quad_perm:[2,3,0,1] row_mask:0xf bank_mask:0xf
	v_cvt_pk_f32_fp8_sdwa v[228:229], v55 src0_sel:WORD_1
	v_pk_mul_f32 v[128:129], v[214:215], v[182:183]
	v_pk_mul_f32 v[130:131], v[216:217], v[184:185]
	v_pk_fma_f32 v[128:129], v[186:187], v[218:219], v[128:129]
	v_pk_fma_f32 v[130:131], v[188:189], v[220:221], v[130:131]
	v_pk_fma_f32 v[128:129], v[190:191], v[222:223], v[128:129]
	v_pk_fma_f32 v[130:131], v[192:193], v[224:225], v[130:131]
	v_pk_fma_f32 v[128:129], v[194:195], v[226:227], v[128:129]
	v_pk_fma_f32 v[130:131], v[196:197], v[228:229], v[130:131]
	buffer_load_dwordx4 v[52:55], v163, s[16:19], s27 offen sc0
	v_pk_add_f32 v[128:129], v[128:129], v[130:131]
	v_add_f32_dpp v162, v132, v132 row_half_mirror row_mask:0xf bank_mask:0xf
	v_add_f32_e32 v133, v128, v129
	s_waitcnt vmcnt(37)
	v_cvt_pk_f32_fp8_e32 v[214:215], v56
	v_cvt_pk_f32_fp8_sdwa v[216:217], v56 src0_sel:WORD_1
	v_cvt_pk_f32_fp8_e32 v[218:219], v57
	v_add_f32_dpp v133, v133, v133 quad_perm:[1,0,3,2] row_mask:0xf bank_mask:0xf
	v_cvt_pk_f32_fp8_sdwa v[220:221], v57 src0_sel:WORD_1
	v_cvt_pk_f32_fp8_e32 v[222:223], v58
	v_cvt_pk_f32_fp8_sdwa v[224:225], v58 src0_sel:WORD_1
	v_cvt_pk_f32_fp8_e32 v[226:227], v59
	v_add_f32_dpp v133, v133, v133 quad_perm:[2,3,0,1] row_mask:0xf bank_mask:0xf
	v_cvt_pk_f32_fp8_sdwa v[228:229], v59 src0_sel:WORD_1
	v_pk_mul_f32 v[128:129], v[214:215], v[182:183]
	v_pk_mul_f32 v[130:131], v[216:217], v[184:185]
	v_pk_fma_f32 v[128:129], v[186:187], v[218:219], v[128:129]
	v_pk_fma_f32 v[130:131], v[188:189], v[220:221], v[130:131]
	v_pk_fma_f32 v[128:129], v[190:191], v[222:223], v[128:129]
	v_pk_fma_f32 v[130:131], v[192:193], v[224:225], v[130:131]
	v_pk_fma_f32 v[128:129], v[194:195], v[226:227], v[128:129]
	v_pk_fma_f32 v[130:131], v[196:197], v[228:229], v[130:131]
	buffer_load_dwordx4 v[56:59], v164, s[16:19], s27 offen sc0
	v_pk_add_f32 v[128:129], v[128:129], v[130:131]
	v_add_f32_dpp v163, v133, v133 row_half_mirror row_mask:0xf bank_mask:0xf
	v_add_f32_e32 v132, v128, v129
	s_waitcnt vmcnt(37)
	v_cvt_pk_f32_fp8_e32 v[214:215], v60
	v_cvt_pk_f32_fp8_sdwa v[216:217], v60 src0_sel:WORD_1
	v_cvt_pk_f32_fp8_e32 v[218:219], v61
	v_add_f32_dpp v132, v132, v132 quad_perm:[1,0,3,2] row_mask:0xf bank_mask:0xf
	v_cvt_pk_f32_fp8_sdwa v[220:221], v61 src0_sel:WORD_1
	v_cvt_pk_f32_fp8_e32 v[222:223], v62
	v_cvt_pk_f32_fp8_sdwa v[224:225], v62 src0_sel:WORD_1
	v_cvt_pk_f32_fp8_e32 v[226:227], v63
	v_add_f32_dpp v132, v132, v132 quad_perm:[2,3,0,1] row_mask:0xf bank_mask:0xf
	v_cvt_pk_f32_fp8_sdwa v[228:229], v63 src0_sel:WORD_1
	v_pk_mul_f32 v[128:129], v[214:215], v[182:183]
	v_pk_mul_f32 v[130:131], v[216:217], v[184:185]
	v_pk_fma_f32 v[128:129], v[186:187], v[218:219], v[128:129]
	v_pk_fma_f32 v[130:131], v[188:189], v[220:221], v[130:131]
	v_pk_fma_f32 v[128:129], v[190:191], v[222:223], v[128:129]
	v_pk_fma_f32 v[130:131], v[192:193], v[224:225], v[130:131]
	v_pk_fma_f32 v[128:129], v[194:195], v[226:227], v[128:129]
	v_pk_fma_f32 v[130:131], v[196:197], v[228:229], v[130:131]
	buffer_load_dwordx4 v[60:63], v165, s[16:19], s27 offen sc0
	v_pk_add_f32 v[128:129], v[128:129], v[130:131]
	v_add_f32_dpp v164, v132, v132 row_half_mirror row_mask:0xf bank_mask:0xf
	v_add_f32_e32 v133, v128, v129
	s_waitcnt vmcnt(37)
	v_cvt_pk_f32_fp8_e32 v[214:215], v64
	v_cvt_pk_f32_fp8_sdwa v[216:217], v64 src0_sel:WORD_1
	v_cvt_pk_f32_fp8_e32 v[218:219], v65
	v_add_f32_dpp v133, v133, v133 quad_perm:[1,0,3,2] row_mask:0xf bank_mask:0xf
	v_cvt_pk_f32_fp8_sdwa v[220:221], v65 src0_sel:WORD_1
	v_cvt_pk_f32_fp8_e32 v[222:223], v66
	v_cvt_pk_f32_fp8_sdwa v[224:225], v66 src0_sel:WORD_1
	v_cvt_pk_f32_fp8_e32 v[226:227], v67
	v_add_f32_dpp v133, v133, v133 quad_perm:[2,3,0,1] row_mask:0xf bank_mask:0xf
	v_cvt_pk_f32_fp8_sdwa v[228:229], v67 src0_sel:WORD_1
	v_pk_mul_f32 v[128:129], v[214:215], v[182:183]
	v_pk_mul_f32 v[130:131], v[216:217], v[184:185]
	v_pk_fma_f32 v[128:129], v[186:187], v[218:219], v[128:129]
	v_pk_fma_f32 v[130:131], v[188:189], v[220:221], v[130:131]
	v_pk_fma_f32 v[128:129], v[190:191], v[222:223], v[128:129]
	v_pk_fma_f32 v[130:131], v[192:193], v[224:225], v[130:131]
	v_pk_fma_f32 v[128:129], v[194:195], v[226:227], v[128:129]
	v_pk_fma_f32 v[130:131], v[196:197], v[228:229], v[130:131]
	buffer_load_dwordx4 v[64:67], v166, s[16:19], s27 offen sc0
	v_pk_add_f32 v[128:129], v[128:129], v[130:131]
	v_add_f32_dpp v165, v133, v133 row_half_mirror row_mask:0xf bank_mask:0xf
	v_add_f32_e32 v132, v128, v129
	s_waitcnt vmcnt(37)
	v_cvt_pk_f32_fp8_e32 v[214:215], v68
	v_cvt_pk_f32_fp8_sdwa v[216:217], v68 src0_sel:WORD_1
	v_cvt_pk_f32_fp8_e32 v[218:219], v69
	v_add_f32_dpp v132, v132, v132 quad_perm:[1,0,3,2] row_mask:0xf bank_mask:0xf
	v_cvt_pk_f32_fp8_sdwa v[220:221], v69 src0_sel:WORD_1
	v_cvt_pk_f32_fp8_e32 v[222:223], v70
	v_cvt_pk_f32_fp8_sdwa v[224:225], v70 src0_sel:WORD_1
	v_cvt_pk_f32_fp8_e32 v[226:227], v71
	v_add_f32_dpp v132, v132, v132 quad_perm:[2,3,0,1] row_mask:0xf bank_mask:0xf
	v_cvt_pk_f32_fp8_sdwa v[228:229], v71 src0_sel:WORD_1
	v_pk_mul_f32 v[128:129], v[214:215], v[182:183]
	v_pk_mul_f32 v[130:131], v[216:217], v[184:185]
	v_pk_fma_f32 v[128:129], v[186:187], v[218:219], v[128:129]
	v_pk_fma_f32 v[130:131], v[188:189], v[220:221], v[130:131]
	v_pk_fma_f32 v[128:129], v[190:191], v[222:223], v[128:129]
	v_pk_fma_f32 v[130:131], v[192:193], v[224:225], v[130:131]
	v_pk_fma_f32 v[128:129], v[194:195], v[226:227], v[128:129]
	v_pk_fma_f32 v[130:131], v[196:197], v[228:229], v[130:131]
	buffer_load_dwordx4 v[68:71], v167, s[16:19], s27 offen sc0
	v_pk_add_f32 v[128:129], v[128:129], v[130:131]
	v_add_f32_dpp v166, v132, v132 row_half_mirror row_mask:0xf bank_mask:0xf
	v_add_f32_e32 v133, v128, v129
	s_waitcnt vmcnt(37)
; __device__ __forceinline__ float red8(float v) { v += dpp_f<0xB1>(v); v += dpp_f<0x4E>(v); v += dpp_f<0x141>(v); return v; }
; __device__ __forceinline__ void kv8_qk(const u32x4 (&buf)[8], const f32x2v (&q2)[8], LAS float* srow, int b, int lane) {
;     ...
;     for (int u = 0; u < 8; ++u) {
;         const u32x4 k = buf[u];
;         f32x2v s0 = q2[0] * __builtin_amdgcn_cvt_pk_f32_fp8(k.x, false), s1 = q2[1] * __builtin_amdgcn_cvt_pk_f32_fp8(k.x, true);
;         s0 = __builtin_elementwise_fma(q2[2], __builtin_amdgcn_cvt_pk_f32_fp8(k.y, false), s0); s1 = __builtin_elementwise_fma(q2[3], __builtin_amdgcn_cvt_pk_f32_fp8(k.y, true), s1);
;         s0 = __builtin_elementwise_fma(q2[4], __builtin_amdgcn_cvt_pk_f32_fp8(k.z, false), s0); s1 = __builtin_elementwise_fma(q2[5], __builtin_amdgcn_cvt_pk_f32_fp8(k.z, true), s1);
;         s0 = __builtin_elementwise_fma(q2[6], __builtin_amdgcn_cvt_pk_f32_fp8(k.w, false), s0); s1 = __builtin_elementwise_fma(q2[7], __builtin_amdgcn_cvt_pk_f32_fp8(k.w, true), s1);
;         const f32x2v t = s0 + s1;
;         const float s = red8(t.x + t.y);
;         if ((lane & 7) == 0) srow[b * 8 + u] = s;
;     }
	v_cvt_pk_f32_fp8_e32 v[214:215], v72
	v_cvt_pk_f32_fp8_sdwa v[216:217], v72 src0_sel:WORD_1
	v_cvt_pk_f32_fp8_e32 v[218:219], v73
	v_add_f32_dpp v133, v133, v133 quad_perm:[1,0,3,2] row_mask:0xf bank_mask:0xf
	v_cvt_pk_f32_fp8_sdwa v[220:221], v73 src0_sel:WORD_1
	v_cvt_pk_f32_fp8_e32 v[222:223], v74
	v_cvt_pk_f32_fp8_sdwa v[224:225], v74 src0_sel:WORD_1
	v_cvt_pk_f32_fp8_e32 v[226:227], v75
	v_add_f32_dpp v133, v133, v133 quad_perm:[2,3,0,1] row_mask:0xf bank_mask:0xf
	v_cvt_pk_f32_fp8_sdwa v[228:229], v75 src0_sel:WORD_1
	v_pk_mul_f32 v[128:129], v[214:215], v[182:183]
	v_pk_mul_f32 v[130:131], v[216:217], v[184:185]
	v_pk_fma_f32 v[128:129], v[186:187], v[218:219], v[128:129]
	v_pk_fma_f32 v[130:131], v[188:189], v[220:221], v[130:131]
	v_pk_fma_f32 v[128:129], v[190:191], v[222:223], v[128:129]
	v_pk_fma_f32 v[130:131], v[192:193], v[224:225], v[130:131]
	v_pk_fma_f32 v[128:129], v[194:195], v[226:227], v[128:129]
	v_pk_fma_f32 v[130:131], v[196:197], v[228:229], v[130:131]
	buffer_load_dwordx4 v[72:75], v168, s[16:19], s27 offen sc0
	v_pk_add_f32 v[128:129], v[128:129], v[130:131]
	v_add_f32_dpp v167, v133, v133 row_half_mirror row_mask:0xf bank_mask:0xf
	v_add_f32_e32 v132, v128, v129
	s_waitcnt vmcnt(37)
	v_cvt_pk_f32_fp8_e32 v[214:215], v76
	v_cvt_pk_f32_fp8_sdwa v[216:217], v76 src0_sel:WORD_1
	v_cvt_pk_f32_fp8_e32 v[218:219], v77
	v_add_f32_dpp v132, v132, v132 quad_perm:[1,0,3,2] row_mask:0xf bank_mask:0xf
	v_cvt_pk_f32_fp8_sdwa v[220:221], v77 src0_sel:WORD_1
	v_cvt_pk_f32_fp8_e32 v[222:223], v78
	v_cvt_pk_f32_fp8_sdwa v[224:225], v78 src0_sel:WORD_1
	v_cvt_pk_f32_fp8_e32 v[226:227], v79
	v_add_f32_dpp v132, v132, v132 quad_perm:[2,3,0,1] row_mask:0xf bank_mask:0xf
	v_cvt_pk_f32_fp8_sdwa v[228:229], v79 src0_sel:WORD_1
	v_pk_mul_f32 v[128:129], v[214:215], v[182:183]
	v_pk_mul_f32 v[130:131], v[216:217], v[184:185]
	v_pk_fma_f32 v[128:129], v[186:187], v[218:219], v[128:129]
	v_pk_fma_f32 v[130:131], v[188:189], v[220:221], v[130:131]
	v_pk_fma_f32 v[128:129], v[190:191], v[222:223], v[128:129]
	v_pk_fma_f32 v[130:131], v[192:193], v[224:225], v[130:131]
	v_pk_fma_f32 v[128:129], v[194:195], v[226:227], v[128:129]
	v_pk_fma_f32 v[130:131], v[196:197], v[228:229], v[130:131]
	buffer_load_dwordx4 v[76:79], v169, s[16:19], s27 offen sc0
	v_pk_add_f32 v[128:129], v[128:129], v[130:131]
	v_add_f32_dpp v168, v132, v132 row_half_mirror row_mask:0xf bank_mask:0xf
	v_add_f32_e32 v133, v128, v129
	s_waitcnt vmcnt(37)
	v_cvt_pk_f32_fp8_e32 v[214:215], v80
	v_cvt_pk_f32_fp8_sdwa v[216:217], v80 src0_sel:WORD_1
	v_cvt_pk_f32_fp8_e32 v[218:219], v81
	v_add_f32_dpp v133, v133, v133 quad_perm:[1,0,3,2] row_mask:0xf bank_mask:0xf
	v_cvt_pk_f32_fp8_sdwa v[220:221], v81 src0_sel:WORD_1
	v_cvt_pk_f32_fp8_e32 v[222:223], v82
	v_cvt_pk_f32_fp8_sdwa v[224:225], v82 src0_sel:WORD_1
	v_cvt_pk_f32_fp8_e32 v[226:227], v83
	v_add_f32_dpp v133, v133, v133 quad_perm:[2,3,0,1] row_mask:0xf bank_mask:0xf
	v_cvt_pk_f32_fp8_sdwa v[228:229], v83 src0_sel:WORD_1
	v_pk_mul_f32 v[128:129], v[214:215], v[182:183]
	v_pk_mul_f32 v[130:131], v[216:217], v[184:185]
	v_pk_fma_f32 v[128:129], v[186:187], v[218:219], v[128:129]
	v_pk_fma_f32 v[130:131], v[188:189], v[220:221], v[130:131]
	v_pk_fma_f32 v[128:129], v[190:191], v[222:223], v[128:129]
	v_pk_fma_f32 v[130:131], v[192:193], v[224:225], v[130:131]
	v_pk_fma_f32 v[128:129], v[194:195], v[226:227], v[128:129]
	v_pk_fma_f32 v[130:131], v[196:197], v[228:229], v[130:131]
	buffer_load_dwordx4 v[80:83], v170, s[16:19], s27 offen sc0
	v_pk_add_f32 v[128:129], v[128:129], v[130:131]
	v_add_f32_dpp v169, v133, v133 row_half_mirror row_mask:0xf bank_mask:0xf
	v_add_f32_e32 v132, v128, v129
	s_waitcnt vmcnt(37)
	v_cvt_pk_f32_fp8_e32 v[214:215], v84
	v_cvt_pk_f32_fp8_sdwa v[216:217], v84 src0_sel:WORD_1
	v_cvt_pk_f32_fp8_e32 v[218:219], v85
	v_add_f32_dpp v132, v132, v132 quad_perm:[1,0,3,2] row_mask:0xf bank_mask:0xf
	v_cvt_pk_f32_fp8_sdwa v[220:221], v85 src0_sel:WORD_1
	v_cvt_pk_f32_fp8_e32 v[222:223], v86
	v_cvt_pk_f32_fp8_sdwa v[224:225], v86 src0_sel:WORD_1
	v_cvt_pk_f32_fp8_e32 v[226:227], v87
	v_add_f32_dpp v132, v132, v132 quad_perm:[2,3,0,1] row_mask:0xf bank_mask:0xf
	v_cvt_pk_f32_fp8_sdwa v[228:229], v87 src0_sel:WORD_1
	v_pk_mul_f32 v[128:129], v[214:215], v[182:183]
	v_pk_mul_f32 v[130:131], v[216:217], v[184:185]
	v_pk_fma_f32 v[128:129], v[186:187], v[218:219], v[128:129]
	v_pk_fma_f32 v[130:131], v[188:189], v[220:221], v[130:131]
	v_pk_fma_f32 v[128:129], v[190:191], v[222:223], v[128:129]
	v_pk_fma_f32 v[130:131], v[192:193], v[224:225], v[130:131]
	v_pk_fma_f32 v[128:129], v[194:195], v[226:227], v[128:129]
	v_pk_fma_f32 v[130:131], v[196:197], v[228:229], v[130:131]
	buffer_load_dwordx4 v[84:87], v171, s[16:19], s27 offen sc0
	v_pk_add_f32 v[128:129], v[128:129], v[130:131]
	v_add_f32_dpp v170, v132, v132 row_half_mirror row_mask:0xf bank_mask:0xf
	v_add_f32_e32 v133, v128, v129
	s_waitcnt vmcnt(37)
	v_cvt_pk_f32_fp8_e32 v[214:215], v88
	v_cvt_pk_f32_fp8_sdwa v[216:217], v88 src0_sel:WORD_1
	v_cvt_pk_f32_fp8_e32 v[218:219], v89
	v_add_f32_dpp v133, v133, v133 quad_perm:[1,0,3,2] row_mask:0xf bank_mask:0xf
	v_cvt_pk_f32_fp8_sdwa v[220:221], v89 src0_sel:WORD_1
	v_cvt_pk_f32_fp8_e32 v[222:223], v90
	v_cvt_pk_f32_fp8_sdwa v[224:225], v90 src0_sel:WORD_1
	v_cvt_pk_f32_fp8_e32 v[226:227], v91
	v_add_f32_dpp v133, v133, v133 quad_perm:[2,3,0,1] row_mask:0xf bank_mask:0xf
	v_cvt_pk_f32_fp8_sdwa v[228:229], v91 src0_sel:WORD_1
	v_pk_mul_f32 v[128:129], v[214:215], v[182:183]
	v_pk_mul_f32 v[130:131], v[216:217], v[184:185]
	v_pk_fma_f32 v[128:129], v[186:187], v[218:219], v[128:129]
	v_pk_fma_f32 v[130:131], v[188:189], v[220:221], v[130:131]
	v_pk_fma_f32 v[128:129], v[190:191], v[222:223], v[128:129]
	v_pk_fma_f32 v[130:131], v[192:193], v[224:225], v[130:131]
	v_pk_fma_f32 v[128:129], v[194:195], v[226:227], v[128:129]
	v_pk_fma_f32 v[130:131], v[196:197], v[228:229], v[130:131]
	buffer_load_dwordx4 v[88:91], v172, s[16:19], s27 offen sc0
	v_pk_add_f32 v[128:129], v[128:129], v[130:131]
	v_add_f32_dpp v171, v133, v133 row_half_mirror row_mask:0xf bank_mask:0xf
	v_add_f32_e32 v132, v128, v129
	s_waitcnt vmcnt(37)
; __device__ __forceinline__ float red8(float v) { v += dpp_f<0xB1>(v); v += dpp_f<0x4E>(v); v += dpp_f<0x141>(v); return v; }
; __device__ __forceinline__ void kv8_qk(const u32x4 (&buf)[8], const f32x2v (&q2)[8], LAS float* srow, int b, int lane) {
;     ...
;     for (int u = 0; u < 8; ++u) {
;         const u32x4 k = buf[u];
;         f32x2v s0 = q2[0] * __builtin_amdgcn_cvt_pk_f32_fp8(k.x, false), s1 = q2[1] * __builtin_amdgcn_cvt_pk_f32_fp8(k.x, true);
;         s0 = __builtin_elementwise_fma(q2[2], __builtin_amdgcn_cvt_pk_f32_fp8(k.y, false), s0); s1 = __builtin_elementwise_fma(q2[3], __builtin_amdgcn_cvt_pk_f32_fp8(k.y, true), s1);
;         s0 = __builtin_elementwise_fma(q2[4], __builtin_amdgcn_cvt_pk_f32_fp8(k.z, false), s0); s1 = __builtin_elementwise_fma(q2[5], __builtin_amdgcn_cvt_pk_f32_fp8(k.z, true), s1);
;         s0 = __builtin_elementwise_fma(q2[6], __builtin_amdgcn_cvt_pk_f32_fp8(k.w, false), s0); s1 = __builtin_elementwise_fma(q2[7], __builtin_amdgcn_cvt_pk_f32_fp8(k.w, true), s1);
;         const f32x2v t = s0 + s1;
;         const float s = red8(t.x + t.y);
;         if ((lane & 7) == 0) srow[b * 8 + u] = s;
;     }
	v_cvt_pk_f32_fp8_e32 v[214:215], v92
	v_cvt_pk_f32_fp8_sdwa v[216:217], v92 src0_sel:WORD_1
	v_cvt_pk_f32_fp8_e32 v[218:219], v93
	v_add_f32_dpp v132, v132, v132 quad_perm:[1,0,3,2] row_mask:0xf bank_mask:0xf
	v_cvt_pk_f32_fp8_sdwa v[220:221], v93 src0_sel:WORD_1
	v_cvt_pk_f32_fp8_e32 v[222:223], v94
	v_cvt_pk_f32_fp8_sdwa v[224:225], v94 src0_sel:WORD_1
	v_cvt_pk_f32_fp8_e32 v[226:227], v95
	v_add_f32_dpp v132, v132, v132 quad_perm:[2,3,0,1] row_mask:0xf bank_mask:0xf
	v_cvt_pk_f32_fp8_sdwa v[228:229], v95 src0_sel:WORD_1
	v_pk_mul_f32 v[128:129], v[214:215], v[182:183]
	v_pk_mul_f32 v[130:131], v[216:217], v[184:185]
	v_pk_fma_f32 v[128:129], v[186:187], v[218:219], v[128:129]
	v_pk_fma_f32 v[130:131], v[188:189], v[220:221], v[130:131]
	v_pk_fma_f32 v[128:129], v[190:191], v[222:223], v[128:129]
	v_pk_fma_f32 v[130:131], v[192:193], v[224:225], v[130:131]
	v_pk_fma_f32 v[128:129], v[194:195], v[226:227], v[128:129]
	v_pk_fma_f32 v[130:131], v[196:197], v[228:229], v[130:131]
	buffer_load_dwordx4 v[92:95], v173, s[16:19], s27 offen sc0
	v_pk_add_f32 v[128:129], v[128:129], v[130:131]
	v_add_f32_dpp v172, v132, v132 row_half_mirror row_mask:0xf bank_mask:0xf
	v_add_f32_e32 v133, v128, v129
	s_waitcnt vmcnt(37)
	v_cvt_pk_f32_fp8_e32 v[214:215], v96
	v_cvt_pk_f32_fp8_sdwa v[216:217], v96 src0_sel:WORD_1
	v_cvt_pk_f32_fp8_e32 v[218:219], v97
	v_add_f32_dpp v133, v133, v133 quad_perm:[1,0,3,2] row_mask:0xf bank_mask:0xf
	v_cvt_pk_f32_fp8_sdwa v[220:221], v97 src0_sel:WORD_1
	v_cvt_pk_f32_fp8_e32 v[222:223], v98
	v_cvt_pk_f32_fp8_sdwa v[224:225], v98 src0_sel:WORD_1
	v_cvt_pk_f32_fp8_e32 v[226:227], v99
	v_add_f32_dpp v133, v133, v133 quad_perm:[2,3,0,1] row_mask:0xf bank_mask:0xf
	v_cvt_pk_f32_fp8_sdwa v[228:229], v99 src0_sel:WORD_1
	v_pk_mul_f32 v[128:129], v[214:215], v[182:183]
	v_pk_mul_f32 v[130:131], v[216:217], v[184:185]
	v_pk_fma_f32 v[128:129], v[186:187], v[218:219], v[128:129]
	v_pk_fma_f32 v[130:131], v[188:189], v[220:221], v[130:131]
	v_pk_fma_f32 v[128:129], v[190:191], v[222:223], v[128:129]
	v_pk_fma_f32 v[130:131], v[192:193], v[224:225], v[130:131]
	v_pk_fma_f32 v[128:129], v[194:195], v[226:227], v[128:129]
	v_pk_fma_f32 v[130:131], v[196:197], v[228:229], v[130:131]
	buffer_load_dwordx4 v[96:99], v174, s[16:19], s27 offen sc0
	v_pk_add_f32 v[128:129], v[128:129], v[130:131]
	v_add_f32_dpp v173, v133, v133 row_half_mirror row_mask:0xf bank_mask:0xf
	v_add_f32_e32 v132, v128, v129
	s_waitcnt vmcnt(37)
	v_cvt_pk_f32_fp8_e32 v[214:215], v100
	v_cvt_pk_f32_fp8_sdwa v[216:217], v100 src0_sel:WORD_1
	v_cvt_pk_f32_fp8_e32 v[218:219], v101
	v_add_f32_dpp v132, v132, v132 quad_perm:[1,0,3,2] row_mask:0xf bank_mask:0xf
	v_cvt_pk_f32_fp8_sdwa v[220:221], v101 src0_sel:WORD_1
	v_cvt_pk_f32_fp8_e32 v[222:223], v102
	v_cvt_pk_f32_fp8_sdwa v[224:225], v102 src0_sel:WORD_1
	v_cvt_pk_f32_fp8_e32 v[226:227], v103
	v_add_f32_dpp v132, v132, v132 quad_perm:[2,3,0,1] row_mask:0xf bank_mask:0xf
	v_cvt_pk_f32_fp8_sdwa v[228:229], v103 src0_sel:WORD_1
	v_pk_mul_f32 v[128:129], v[214:215], v[182:183]
	v_pk_mul_f32 v[130:131], v[216:217], v[184:185]
	v_pk_fma_f32 v[128:129], v[186:187], v[218:219], v[128:129]
	v_pk_fma_f32 v[130:131], v[188:189], v[220:221], v[130:131]
	v_pk_fma_f32 v[128:129], v[190:191], v[222:223], v[128:129]
	v_pk_fma_f32 v[130:131], v[192:193], v[224:225], v[130:131]
	v_pk_fma_f32 v[128:129], v[194:195], v[226:227], v[128:129]
	v_pk_fma_f32 v[130:131], v[196:197], v[228:229], v[130:131]
	buffer_load_dwordx4 v[100:103], v175, s[16:19], s27 offen sc0
	v_pk_add_f32 v[128:129], v[128:129], v[130:131]
	v_add_f32_dpp v174, v132, v132 row_half_mirror row_mask:0xf bank_mask:0xf
	v_add_f32_e32 v133, v128, v129
	s_waitcnt vmcnt(37)
	v_cvt_pk_f32_fp8_e32 v[214:215], v104
	v_cvt_pk_f32_fp8_sdwa v[216:217], v104 src0_sel:WORD_1
	v_cvt_pk_f32_fp8_e32 v[218:219], v105
	v_add_f32_dpp v133, v133, v133 quad_perm:[1,0,3,2] row_mask:0xf bank_mask:0xf
	v_cvt_pk_f32_fp8_sdwa v[220:221], v105 src0_sel:WORD_1
	v_cvt_pk_f32_fp8_e32 v[222:223], v106
	v_cvt_pk_f32_fp8_sdwa v[224:225], v106 src0_sel:WORD_1
	v_cvt_pk_f32_fp8_e32 v[226:227], v107
	v_add_f32_dpp v133, v133, v133 quad_perm:[2,3,0,1] row_mask:0xf bank_mask:0xf
	v_cvt_pk_f32_fp8_sdwa v[228:229], v107 src0_sel:WORD_1
	v_pk_mul_f32 v[128:129], v[214:215], v[182:183]
	v_pk_mul_f32 v[130:131], v[216:217], v[184:185]
	v_pk_fma_f32 v[128:129], v[186:187], v[218:219], v[128:129]
	v_pk_fma_f32 v[130:131], v[188:189], v[220:221], v[130:131]
	v_pk_fma_f32 v[128:129], v[190:191], v[222:223], v[128:129]
	v_pk_fma_f32 v[130:131], v[192:193], v[224:225], v[130:131]
	v_pk_fma_f32 v[128:129], v[194:195], v[226:227], v[128:129]
	v_pk_fma_f32 v[130:131], v[196:197], v[228:229], v[130:131]
	buffer_load_dwordx4 v[104:107], v176, s[16:19], s27 offen sc0
	v_pk_add_f32 v[128:129], v[128:129], v[130:131]
	v_add_f32_dpp v175, v133, v133 row_half_mirror row_mask:0xf bank_mask:0xf
	v_add_f32_e32 v132, v128, v129
	s_waitcnt vmcnt(37)
	v_cvt_pk_f32_fp8_e32 v[214:215], v108
	v_cvt_pk_f32_fp8_sdwa v[216:217], v108 src0_sel:WORD_1
	v_cvt_pk_f32_fp8_e32 v[218:219], v109
	v_add_f32_dpp v132, v132, v132 quad_perm:[1,0,3,2] row_mask:0xf bank_mask:0xf
	v_cvt_pk_f32_fp8_sdwa v[220:221], v109 src0_sel:WORD_1
	v_cvt_pk_f32_fp8_e32 v[222:223], v110
	v_cvt_pk_f32_fp8_sdwa v[224:225], v110 src0_sel:WORD_1
	v_cvt_pk_f32_fp8_e32 v[226:227], v111
	v_add_f32_dpp v132, v132, v132 quad_perm:[2,3,0,1] row_mask:0xf bank_mask:0xf
	v_cvt_pk_f32_fp8_sdwa v[228:229], v111 src0_sel:WORD_1
	v_pk_mul_f32 v[128:129], v[214:215], v[182:183]
	v_pk_mul_f32 v[130:131], v[216:217], v[184:185]
	v_pk_fma_f32 v[128:129], v[186:187], v[218:219], v[128:129]
	v_pk_fma_f32 v[130:131], v[188:189], v[220:221], v[130:131]
	v_pk_fma_f32 v[128:129], v[190:191], v[222:223], v[128:129]
	v_pk_fma_f32 v[130:131], v[192:193], v[224:225], v[130:131]
	v_pk_fma_f32 v[128:129], v[194:195], v[226:227], v[128:129]
	v_pk_fma_f32 v[130:131], v[196:197], v[228:229], v[130:131]
	buffer_load_dwordx4 v[108:111], v177, s[16:19], s27 offen sc0
	v_pk_add_f32 v[128:129], v[128:129], v[130:131]
	v_add_f32_dpp v176, v132, v132 row_half_mirror row_mask:0xf bank_mask:0xf
	v_add_f32_e32 v133, v128, v129
	s_waitcnt vmcnt(37)
; __device__ __forceinline__ float red8(float v) { v += dpp_f<0xB1>(v); v += dpp_f<0x4E>(v); v += dpp_f<0x141>(v); return v; }
; __device__ __forceinline__ void kv8_qk(const u32x4 (&buf)[8], const f32x2v (&q2)[8], LAS float* srow, int b, int lane) {
;     ...
;     for (int u = 0; u < 8; ++u) {
;         const u32x4 k = buf[u];
;         f32x2v s0 = q2[0] * __builtin_amdgcn_cvt_pk_f32_fp8(k.x, false), s1 = q2[1] * __builtin_amdgcn_cvt_pk_f32_fp8(k.x, true);
;         s0 = __builtin_elementwise_fma(q2[2], __builtin_amdgcn_cvt_pk_f32_fp8(k.y, false), s0); s1 = __builtin_elementwise_fma(q2[3], __builtin_amdgcn_cvt_pk_f32_fp8(k.y, true), s1);
;         s0 = __builtin_elementwise_fma(q2[4], __builtin_amdgcn_cvt_pk_f32_fp8(k.z, false), s0); s1 = __builtin_elementwise_fma(q2[5], __builtin_amdgcn_cvt_pk_f32_fp8(k.z, true), s1);
;         s0 = __builtin_elementwise_fma(q2[6], __builtin_amdgcn_cvt_pk_f32_fp8(k.w, false), s0); s1 = __builtin_elementwise_fma(q2[7], __builtin_amdgcn_cvt_pk_f32_fp8(k.w, true), s1);
;         const f32x2v t = s0 + s1;
;         const float s = red8(t.x + t.y);
;         if ((lane & 7) == 0) srow[b * 8 + u] = s;
;     }
	v_cvt_pk_f32_fp8_e32 v[214:215], v112
	v_cvt_pk_f32_fp8_sdwa v[216:217], v112 src0_sel:WORD_1
	v_cvt_pk_f32_fp8_e32 v[218:219], v113
	v_add_f32_dpp v133, v133, v133 quad_perm:[1,0,3,2] row_mask:0xf bank_mask:0xf
	v_cvt_pk_f32_fp8_sdwa v[220:221], v113 src0_sel:WORD_1
	v_cvt_pk_f32_fp8_e32 v[222:223], v114
	v_cvt_pk_f32_fp8_sdwa v[224:225], v114 src0_sel:WORD_1
	v_cvt_pk_f32_fp8_e32 v[226:227], v115
	v_add_f32_dpp v133, v133, v133 quad_perm:[2,3,0,1] row_mask:0xf bank_mask:0xf
	v_cvt_pk_f32_fp8_sdwa v[228:229], v115 src0_sel:WORD_1
	v_pk_mul_f32 v[128:129], v[214:215], v[182:183]
	v_pk_mul_f32 v[130:131], v[216:217], v[184:185]
	v_pk_fma_f32 v[128:129], v[186:187], v[218:219], v[128:129]
	v_pk_fma_f32 v[130:131], v[188:189], v[220:221], v[130:131]
	v_pk_fma_f32 v[128:129], v[190:191], v[222:223], v[128:129]
	v_pk_fma_f32 v[130:131], v[192:193], v[224:225], v[130:131]
	v_pk_fma_f32 v[128:129], v[194:195], v[226:227], v[128:129]
	v_pk_fma_f32 v[130:131], v[196:197], v[228:229], v[130:131]
	buffer_load_dwordx4 v[112:115], v178, s[16:19], s27 offen sc0
	v_pk_add_f32 v[128:129], v[128:129], v[130:131]
	v_add_f32_dpp v177, v133, v133 row_half_mirror row_mask:0xf bank_mask:0xf
	v_add_f32_e32 v132, v128, v129
	s_waitcnt vmcnt(37)
	v_cvt_pk_f32_fp8_e32 v[214:215], v116
	v_cvt_pk_f32_fp8_sdwa v[216:217], v116 src0_sel:WORD_1
	v_cvt_pk_f32_fp8_e32 v[218:219], v117
	v_add_f32_dpp v132, v132, v132 quad_perm:[1,0,3,2] row_mask:0xf bank_mask:0xf
	v_cvt_pk_f32_fp8_sdwa v[220:221], v117 src0_sel:WORD_1
	v_cvt_pk_f32_fp8_e32 v[222:223], v118
	v_cvt_pk_f32_fp8_sdwa v[224:225], v118 src0_sel:WORD_1
	v_cvt_pk_f32_fp8_e32 v[226:227], v119
	v_add_f32_dpp v132, v132, v132 quad_perm:[2,3,0,1] row_mask:0xf bank_mask:0xf
	v_cvt_pk_f32_fp8_sdwa v[228:229], v119 src0_sel:WORD_1
	v_pk_mul_f32 v[128:129], v[214:215], v[182:183]
	v_pk_mul_f32 v[130:131], v[216:217], v[184:185]
	v_pk_fma_f32 v[128:129], v[186:187], v[218:219], v[128:129]
	v_pk_fma_f32 v[130:131], v[188:189], v[220:221], v[130:131]
	v_pk_fma_f32 v[128:129], v[190:191], v[222:223], v[128:129]
	v_pk_fma_f32 v[130:131], v[192:193], v[224:225], v[130:131]
	v_pk_fma_f32 v[128:129], v[194:195], v[226:227], v[128:129]
	v_pk_fma_f32 v[130:131], v[196:197], v[228:229], v[130:131]
	buffer_load_dwordx4 v[116:119], v179, s[16:19], s27 offen sc0
	v_pk_add_f32 v[128:129], v[128:129], v[130:131]
	v_add_f32_dpp v178, v132, v132 row_half_mirror row_mask:0xf bank_mask:0xf
	v_add_f32_e32 v133, v128, v129
	s_waitcnt vmcnt(37)
	v_cvt_pk_f32_fp8_e32 v[214:215], v120
	v_cvt_pk_f32_fp8_sdwa v[216:217], v120 src0_sel:WORD_1
	v_cvt_pk_f32_fp8_e32 v[218:219], v121
	v_add_f32_dpp v133, v133, v133 quad_perm:[1,0,3,2] row_mask:0xf bank_mask:0xf
	v_cvt_pk_f32_fp8_sdwa v[220:221], v121 src0_sel:WORD_1
	v_cvt_pk_f32_fp8_e32 v[222:223], v122
	v_cvt_pk_f32_fp8_sdwa v[224:225], v122 src0_sel:WORD_1
	v_cvt_pk_f32_fp8_e32 v[226:227], v123
	v_add_f32_dpp v133, v133, v133 quad_perm:[2,3,0,1] row_mask:0xf bank_mask:0xf
	v_cvt_pk_f32_fp8_sdwa v[228:229], v123 src0_sel:WORD_1
	v_pk_mul_f32 v[128:129], v[214:215], v[182:183]
	v_pk_mul_f32 v[130:131], v[216:217], v[184:185]
	v_pk_fma_f32 v[128:129], v[186:187], v[218:219], v[128:129]
	v_pk_fma_f32 v[130:131], v[188:189], v[220:221], v[130:131]
	v_pk_fma_f32 v[128:129], v[190:191], v[222:223], v[128:129]
	v_pk_fma_f32 v[130:131], v[192:193], v[224:225], v[130:131]
	v_pk_fma_f32 v[128:129], v[194:195], v[226:227], v[128:129]
	v_pk_fma_f32 v[130:131], v[196:197], v[228:229], v[130:131]
	buffer_load_dwordx4 v[120:123], v180, s[16:19], s27 offen sc0
	v_pk_add_f32 v[128:129], v[128:129], v[130:131]
	v_add_f32_dpp v179, v133, v133 row_half_mirror row_mask:0xf bank_mask:0xf
	v_add_f32_e32 v132, v128, v129
	s_waitcnt vmcnt(37)
	v_cvt_pk_f32_fp8_e32 v[214:215], v124
	v_cvt_pk_f32_fp8_sdwa v[216:217], v124 src0_sel:WORD_1
	v_cvt_pk_f32_fp8_e32 v[218:219], v125
	v_add_f32_dpp v132, v132, v132 quad_perm:[1,0,3,2] row_mask:0xf bank_mask:0xf
	v_cvt_pk_f32_fp8_sdwa v[220:221], v125 src0_sel:WORD_1
	v_cvt_pk_f32_fp8_e32 v[222:223], v126
	v_cvt_pk_f32_fp8_sdwa v[224:225], v126 src0_sel:WORD_1
	v_cvt_pk_f32_fp8_e32 v[226:227], v127
	v_add_f32_dpp v132, v132, v132 quad_perm:[2,3,0,1] row_mask:0xf bank_mask:0xf
	v_cvt_pk_f32_fp8_sdwa v[228:229], v127 src0_sel:WORD_1
	v_pk_mul_f32 v[128:129], v[214:215], v[182:183]
	v_pk_mul_f32 v[130:131], v[216:217], v[184:185]
	v_pk_fma_f32 v[128:129], v[186:187], v[218:219], v[128:129]
	v_pk_fma_f32 v[130:131], v[188:189], v[220:221], v[130:131]
	v_pk_fma_f32 v[128:129], v[190:191], v[222:223], v[128:129]
	v_pk_fma_f32 v[130:131], v[192:193], v[224:225], v[130:131]
	v_pk_fma_f32 v[128:129], v[194:195], v[226:227], v[128:129]
	v_pk_fma_f32 v[130:131], v[196:197], v[228:229], v[130:131]
	buffer_load_dwordx4 v[124:127], v181, s[16:19], s27 offen sc0
	v_pk_add_f32 v[128:129], v[128:129], v[130:131]
	v_add_f32_dpp v180, v132, v132 row_half_mirror row_mask:0xf bank_mask:0xf
	v_add_f32_e32 v133, v128, v129
	s_nop 1
	v_add_f32_dpp v133, v133, v133 quad_perm:[1,0,3,2] row_mask:0xf bank_mask:0xf
	s_nop 1
	v_add_f32_dpp v133, v133, v133 quad_perm:[2,3,0,1] row_mask:0xf bank_mask:0xf
	s_nop 1
	v_add_f32_dpp v181, v133, v133 row_half_mirror row_mask:0xf bank_mask:0xf
	s_cmpk_eq_i32 s4, 0x100
	s_cbranch_scc1 .Latt_nomask
; __device__ __forceinline__ void attn_query8(const unsigned char* __restrict__ KV8, const bf16_t* __restrict__ Z, const int* __restrict__ SEL, bf16_t* __restrict__ YMIX, int t, LAS float* sbuf  ) {
;     ...
;     for (int h = 0; h < 8; ++h) {
;         float sv[4]; float mx = -__builtin_inff();
; #pragma unroll
;         for (int jj = 0; jj < 4; ++jj) { const int j = lane + 64 * jj; const float s = sbuf[h * 256 + j]; sv[jj] = (j < nsel) ? s : -__builtin_inff(); mx = fmaxf(mx, sv[jj]); }
;         mx = wave_max(mx); float sm = 0.f;
; #pragma unroll
;         for (int jj = 0; jj < 4; ++jj) { const int j = lane + 64 * jj; sv[jj] = (j < nsel) ? __expf(sv[jj] - mx) : 0.f; sm += sv[jj]; }
;         sm = wave_sum(sm); const float inv = 1.f / sm;
; #pragma unroll
;         for (int jj = 0; jj < 4; ++jj) sbuf[h * 256 + lane + 64 * jj] = sv[jj] * inv;
;     }
	v_cmp_lt_i32_e32 vcc, 0, v143
	s_nop 1
	v_cndmask_b32_e32 v150, v142, v150, vcc
	v_cmp_lt_i32_e32 vcc, 8, v143
	s_nop 1
	v_cndmask_b32_e32 v151, v142, v151, vcc
	v_cmp_lt_i32_e32 vcc, 16, v143
	s_nop 1
	v_cndmask_b32_e32 v152, v142, v152, vcc
	v_cmp_lt_i32_e32 vcc, 24, v143
	s_nop 1
	v_cndmask_b32_e32 v153, v142, v153, vcc
	v_cmp_lt_i32_e32 vcc, 32, v143
	s_nop 1
	v_cndmask_b32_e32 v154, v142, v154, vcc
	v_cmp_lt_i32_e32 vcc, 40, v143
	s_nop 1
	v_cndmask_b32_e32 v155, v142, v155, vcc
	v_cmp_lt_i32_e32 vcc, 48, v143
	s_nop 1
	v_cndmask_b32_e32 v156, v142, v156, vcc
	v_cmp_lt_i32_e32 vcc, 56, v143
	s_nop 1
	v_cndmask_b32_e32 v157, v142, v157, vcc
	v_cmp_lt_i32_e32 vcc, 64, v143
	s_nop 1
	v_cndmask_b32_e32 v158, v142, v158, vcc
	v_cmp_lt_i32_e32 vcc, 0x48, v143
	s_nop 1
	v_cndmask_b32_e32 v159, v142, v159, vcc
	v_cmp_lt_i32_e32 vcc, 0x50, v143
	s_nop 1
	v_cndmask_b32_e32 v160, v142, v160, vcc
	v_cmp_lt_i32_e32 vcc, 0x58, v143
	s_nop 1
	v_cndmask_b32_e32 v161, v142, v161, vcc
	v_cmp_lt_i32_e32 vcc, 0x60, v143
	s_nop 1
	v_cndmask_b32_e32 v162, v142, v162, vcc
	v_cmp_lt_i32_e32 vcc, 0x68, v143
	s_nop 1
	v_cndmask_b32_e32 v163, v142, v163, vcc
	v_cmp_lt_i32_e32 vcc, 0x70, v143
	s_nop 1
	v_cndmask_b32_e32 v164, v142, v164, vcc
	v_cmp_lt_i32_e32 vcc, 0x78, v143
	s_nop 1
	v_cndmask_b32_e32 v165, v142, v165, vcc
	v_cmp_lt_i32_e32 vcc, 0x80, v143
	s_nop 1
	v_cndmask_b32_e32 v166, v142, v166, vcc
	v_cmp_lt_i32_e32 vcc, 0x88, v143
	s_nop 1
	v_cndmask_b32_e32 v167, v142, v167, vcc
	v_cmp_lt_i32_e32 vcc, 0x90, v143
	s_nop 1
	v_cndmask_b32_e32 v168, v142, v168, vcc
	v_cmp_lt_i32_e32 vcc, 0x98, v143
	s_nop 1
	v_cndmask_b32_e32 v169, v142, v169, vcc
	v_cmp_lt_i32_e32 vcc, 0xa0, v143
	s_nop 1
	v_cndmask_b32_e32 v170, v142, v170, vcc
	v_cmp_lt_i32_e32 vcc, 0xa8, v143
	s_nop 1
	v_cndmask_b32_e32 v171, v142, v171, vcc
	v_cmp_lt_i32_e32 vcc, 0xb0, v143
	s_nop 1
	v_cndmask_b32_e32 v172, v142, v172, vcc
	v_cmp_lt_i32_e32 vcc, 0xb8, v143
	s_nop 1
	v_cndmask_b32_e32 v173, v142, v173, vcc
	v_cmp_lt_i32_e32 vcc, 0xc0, v143
	s_nop 1
	v_cndmask_b32_e32 v174, v142, v174, vcc
	v_cmp_lt_i32_e32 vcc, 0xc8, v143
	s_nop 1
	v_cndmask_b32_e32 v175, v142, v175, vcc
	v_cmp_lt_i32_e32 vcc, 0xd0, v143
	s_nop 1
	v_cndmask_b32_e32 v176, v142, v176, vcc
	v_cmp_lt_i32_e32 vcc, 0xd8, v143
	s_nop 1
	v_cndmask_b32_e32 v177, v142, v177, vcc
	v_cmp_lt_i32_e32 vcc, 0xe0, v143
	s_nop 1
	v_cndmask_b32_e32 v178, v142, v178, vcc
	v_cmp_lt_i32_e32 vcc, 0xe8, v143
	s_nop 1
	v_cndmask_b32_e32 v179, v142, v179, vcc
	v_cmp_lt_i32_e32 vcc, 0xf0, v143
	s_nop 1
	v_cndmask_b32_e32 v180, v142, v180, vcc
	v_cmp_lt_i32_e32 vcc, 0xf8, v143
	s_nop 1
	v_cndmask_b32_e32 v181, v142, v181, vcc
.Latt_nomask:
	v_max3_f32 v134, v150, v151, v152
	v_max3_f32 v134, v134, v153, v154
	v_max3_f32 v134, v134, v155, v156
	v_max3_f32 v134, v134, v157, v158
	v_max3_f32 v134, v134, v159, v160
	v_max3_f32 v134, v134, v161, v162
	v_max3_f32 v134, v134, v163, v164
	v_max3_f32 v134, v134, v165, v166
	v_max3_f32 v134, v134, v167, v168
	v_max3_f32 v134, v134, v169, v170
	v_max3_f32 v134, v134, v171, v172
	v_max3_f32 v134, v134, v173, v174
	v_max3_f32 v134, v134, v175, v176
	v_max3_f32 v134, v134, v177, v178
	v_max3_f32 v134, v134, v179, v180
	v_max_f32_e32 v134, v134, v181
	s_nop 1
	v_mov_b32_dpp v135, v134 row_ror:8 row_mask:0xf bank_mask:0xf
	s_nop 0
	v_max_f32_e32 v134, v134, v135
	ds_bpermute_b32 v135, v140, v134
	s_waitcnt lgkmcnt(0)
	v_max_f32_e32 v134, v134, v135
	ds_bpermute_b32 v135, v141, v134
	s_waitcnt lgkmcnt(0)
	v_max_f32_e32 v134, v134, v135
	v_mul_f32_e32 v134, 0xbfb8aa3b, v134
	v_fma_f32 v150, v150, s28, v134
	v_fma_f32 v151, v151, s28, v134
	v_fma_f32 v152, v152, s28, v134
	v_fma_f32 v153, v153, s28, v134
	v_fma_f32 v154, v154, s28, v134
	v_fma_f32 v155, v155, s28, v134
	v_fma_f32 v156, v156, s28, v134
	v_fma_f32 v157, v157, s28, v134
	v_fma_f32 v158, v158, s28, v134
	v_fma_f32 v159, v159, s28, v134
	v_fma_f32 v160, v160, s28, v134
	v_fma_f32 v161, v161, s28, v134
	v_fma_f32 v162, v162, s28, v134
	v_fma_f32 v163, v163, s28, v134
	v_fma_f32 v164, v164, s28, v134
	v_fma_f32 v165, v165, s28, v134
	v_fma_f32 v166, v166, s28, v134
	v_fma_f32 v167, v167, s28, v134
	v_fma_f32 v168, v168, s28, v134
	v_fma_f32 v169, v169, s28, v134
	v_fma_f32 v170, v170, s28, v134
	v_fma_f32 v171, v171, s28, v134
	v_fma_f32 v172, v172, s28, v134
	v_fma_f32 v173, v173, s28, v134
	v_fma_f32 v174, v174, s28, v134
	v_fma_f32 v175, v175, s28, v134
	v_fma_f32 v176, v176, s28, v134
	v_fma_f32 v177, v177, s28, v134
	v_fma_f32 v178, v178, s28, v134
	v_fma_f32 v179, v179, s28, v134
	v_fma_f32 v180, v180, s28, v134
	v_fma_f32 v181, v181, s28, v134
	v_exp_f32_e32 v150, v150
	v_exp_f32_e32 v151, v151
	v_exp_f32_e32 v152, v152
	v_exp_f32_e32 v153, v153
	v_exp_f32_e32 v154, v154
	v_exp_f32_e32 v155, v155
	v_exp_f32_e32 v156, v156
	v_exp_f32_e32 v157, v157
	v_exp_f32_e32 v158, v158
	v_exp_f32_e32 v159, v159
	v_exp_f32_e32 v160, v160
	v_exp_f32_e32 v161, v161
	v_exp_f32_e32 v162, v162
	v_exp_f32_e32 v163, v163
	v_exp_f32_e32 v164, v164
	v_exp_f32_e32 v165, v165
	v_exp_f32_e32 v166, v166
	v_exp_f32_e32 v167, v167
	v_exp_f32_e32 v168, v168
	v_exp_f32_e32 v169, v169
	v_exp_f32_e32 v170, v170
	v_exp_f32_e32 v171, v171
	v_exp_f32_e32 v172, v172
	v_exp_f32_e32 v173, v173
	v_exp_f32_e32 v174, v174
	v_exp_f32_e32 v175, v175
	v_exp_f32_e32 v176, v176
	v_exp_f32_e32 v177, v177
	v_exp_f32_e32 v178, v178
	v_exp_f32_e32 v179, v179
	v_exp_f32_e32 v180, v180
	v_exp_f32_e32 v181, v181
	s_nop 0
	v_add_f32_e32 v134, v150, v151
	v_add_f32_e32 v134, v134, v152
	v_add_f32_e32 v134, v134, v153
	v_add_f32_e32 v134, v134, v154
	v_add_f32_e32 v134, v134, v155
	v_add_f32_e32 v134, v134, v156
	v_add_f32_e32 v134, v134, v157
	v_add_f32_e32 v134, v134, v158
	v_add_f32_e32 v134, v134, v159
	v_add_f32_e32 v134, v134, v160
	v_add_f32_e32 v134, v134, v161
	v_add_f32_e32 v134, v134, v162
	v_add_f32_e32 v134, v134, v163
	v_add_f32_e32 v134, v134, v164
	v_add_f32_e32 v134, v134, v165
	v_add_f32_e32 v134, v134, v166
	v_add_f32_e32 v134, v134, v167
	v_add_f32_e32 v134, v134, v168
	v_add_f32_e32 v134, v134, v169
	v_add_f32_e32 v134, v134, v170
	v_add_f32_e32 v134, v134, v171
	v_add_f32_e32 v134, v134, v172
	v_add_f32_e32 v134, v134, v173
	v_add_f32_e32 v134, v134, v174
	v_add_f32_e32 v134, v134, v175
	v_add_f32_e32 v134, v134, v176
	v_add_f32_e32 v134, v134, v177
	v_add_f32_e32 v134, v134, v178
	v_add_f32_e32 v134, v134, v179
	v_add_f32_e32 v134, v134, v180
	v_add_f32_e32 v134, v134, v181
	s_nop 1
	v_mov_b32_dpp v135, v134 row_ror:8 row_mask:0xf bank_mask:0xf
	s_nop 0
	v_add_f32_e32 v134, v134, v135
	ds_bpermute_b32 v135, v140, v134
	s_waitcnt lgkmcnt(0)
; #define LAS __attribute__((address_space(3)))
; #define LDS_WAIT() asm volatile("s_waitcnt lgkmcnt(0)" ::: "memory")
; __device__ __forceinline__ void kv8_pv(const u32x4 (&buf)[8], f32x2v (&o2)[8], const LAS float* srow, int b) {
;     const LAS f32x4* p4 = (const LAS f32x4*)(srow + b * 8);
;     const f32x4 p0 = p4[0], p1 = p4[1];
;     const float p[8] = {p0.x, p0.y, p0.z, p0.w, p1.x, p1.y, p1.z, p1.w};
; #pragma unroll
;     for (int u = 0; u < 8; ++u) {
;         const u32x4 v = buf[u]; const f32x2v pp = {p[u], p[u]};
;         o2[0] = __builtin_elementwise_fma(pp, __builtin_amdgcn_cvt_pk_f32_fp8(v.x, false), o2[0]); o2[1] = __builtin_elementwise_fma(pp, __builtin_amdgcn_cvt_pk_f32_fp8(v.x, true), o2[1]);
;         o2[2] = __builtin_elementwise_fma(pp, __builtin_amdgcn_cvt_pk_f32_fp8(v.y, false), o2[2]); o2[3] = __builtin_elementwise_fma(pp, __builtin_amdgcn_cvt_pk_f32_fp8(v.y, true), o2[3]);
;         o2[4] = __builtin_elementwise_fma(pp, __builtin_amdgcn_cvt_pk_f32_fp8(v.z, false), o2[4]); o2[5] = __builtin_elementwise_fma(pp, __builtin_amdgcn_cvt_pk_f32_fp8(v.z, true), o2[5]);
;         o2[6] = __builtin_elementwise_fma(pp, __builtin_amdgcn_cvt_pk_f32_fp8(v.w, false), o2[6]); o2[7] = __builtin_elementwise_fma(pp, __builtin_amdgcn_cvt_pk_f32_fp8(v.w, true), o2[7]);
;     }
; __device__ __forceinline__ void attn_query8(const unsigned char* __restrict__ KV8, const bf16_t* __restrict__ Z, const int* __restrict__ SEL, bf16_t* __restrict__ YMIX, int t, LAS float* sbuf  ) {
;     ...
;         sm = wave_sum(sm); const float inv = 1.f / sm;
; #pragma unroll
;         for (int jj = 0; jj < 4; ++jj) sbuf[h * 256 + lane + 64 * jj] = sv[jj] * inv;
;     }
;     LDS_WAIT();
;     f32x2v o[8];
; #pragma unroll
;     for (int i = 0; i < 8; ++i) o[i] = (f32x2v){0.f, 0.f};
; #pragma unroll 1
;     for (int b = 0; b < nb; b += 3) {
;         kv8_issue(C, rs, lvo, 1024, iv, CLAMPB(b + 2));
;         kv8_pv(A, o, srow, b);
;         kv8_issue(A, rs, lvo, 1024, iv, CLAMPB(b + 3));
;         if (b + 1 < nb) kv8_pv(B, o, srow, b + 1);
;         kv8_issue(B, rs, lvo, 1024, iv, CLAMPB(b + 4));
;         if (b + 2 < nb) kv8_pv(C, o, srow, b + 2);
	v_add_f32_e32 v134, v134, v135
	ds_bpermute_b32 v135, v141, v134
	s_waitcnt lgkmcnt(0)
	v_add_f32_e32 v134, v134, v135
	v_div_scale_f32 v132, s[8:9], v134, v134, 1.0
	v_rcp_f32_e32 v135, v132
	v_div_scale_f32 v133, vcc, 1.0, v134, 1.0
	v_fma_f32 v136, -v132, v135, 1.0
	v_fmac_f32_e32 v135, v136, v135
	v_mul_f32_e32 v136, v133, v135
	v_fma_f32 v137, -v132, v136, v133
	v_fmac_f32_e32 v136, v137, v135
	v_fma_f32 v132, -v132, v136, v133
	s_nop 1
	v_div_fmas_f32 v132, v132, v135, v136
	v_div_fixup_f32 v134, v132, v134, 1.0
	v_mov_b32_e32 v149, v134
	v_mov_b32_e32 v198, 0
	v_mov_b32_e32 v199, 0
	v_mov_b32_e32 v200, 0
	v_mov_b32_e32 v201, 0
	v_mov_b32_e32 v202, 0
	v_mov_b32_e32 v203, 0
	v_mov_b32_e32 v204, 0
	v_mov_b32_e32 v205, 0
	v_mov_b32_e32 v206, 0
	v_mov_b32_e32 v207, 0
	v_mov_b32_e32 v208, 0
	v_mov_b32_e32 v209, 0
	v_mov_b32_e32 v210, 0
	v_mov_b32_e32 v211, 0
	v_mov_b32_e32 v212, 0
	v_mov_b32_e32 v213, 0
	s_waitcnt vmcnt(31)
	ds_write_b32 v148, v240 offset:0
	ds_write_b32 v148, v241 offset:32
	ds_write_b32 v148, v242 offset:64
	ds_write_b32 v148, v243 offset:96
	v_cvt_pk_f32_fp8_e32 v[214:215], v0
	v_cvt_pk_f32_fp8_sdwa v[216:217], v0 src0_sel:WORD_1
	v_pk_fma_f32 v[198:199], v[150:151], v[214:215], v[198:199] op_sel_hi:[0,1,1]
	v_pk_fma_f32 v[200:201], v[150:151], v[216:217], v[200:201] op_sel_hi:[0,1,1]
	v_cvt_pk_f32_fp8_e32 v[218:219], v1
	v_cvt_pk_f32_fp8_sdwa v[220:221], v1 src0_sel:WORD_1
	v_pk_fma_f32 v[202:203], v[150:151], v[218:219], v[202:203] op_sel_hi:[0,1,1]
	v_pk_fma_f32 v[204:205], v[150:151], v[220:221], v[204:205] op_sel_hi:[0,1,1]
	v_cvt_pk_f32_fp8_e32 v[214:215], v2
	v_cvt_pk_f32_fp8_sdwa v[216:217], v2 src0_sel:WORD_1
	v_pk_fma_f32 v[206:207], v[150:151], v[214:215], v[206:207] op_sel_hi:[0,1,1]
	v_pk_fma_f32 v[208:209], v[150:151], v[216:217], v[208:209] op_sel_hi:[0,1,1]
	v_cvt_pk_f32_fp8_e32 v[218:219], v3
	v_cvt_pk_f32_fp8_sdwa v[220:221], v3 src0_sel:WORD_1
	v_pk_fma_f32 v[210:211], v[150:151], v[218:219], v[210:211] op_sel_hi:[0,1,1]
	v_pk_fma_f32 v[212:213], v[150:151], v[220:221], v[212:213] op_sel_hi:[0,1,1]
	s_waitcnt vmcnt(30)
	v_cvt_pk_f32_fp8_e32 v[214:215], v4
	v_cvt_pk_f32_fp8_sdwa v[216:217], v4 src0_sel:WORD_1
	v_pk_fma_f32 v[198:199], v[150:151], v[214:215], v[198:199] op_sel:[1,0,0]
	v_pk_fma_f32 v[200:201], v[150:151], v[216:217], v[200:201] op_sel:[1,0,0]
	v_cvt_pk_f32_fp8_e32 v[218:219], v5
	v_cvt_pk_f32_fp8_sdwa v[220:221], v5 src0_sel:WORD_1
	v_pk_fma_f32 v[202:203], v[150:151], v[218:219], v[202:203] op_sel:[1,0,0]
	v_pk_fma_f32 v[204:205], v[150:151], v[220:221], v[204:205] op_sel:[1,0,0]
	v_cvt_pk_f32_fp8_e32 v[214:215], v6
	v_cvt_pk_f32_fp8_sdwa v[216:217], v6 src0_sel:WORD_1
	v_pk_fma_f32 v[206:207], v[150:151], v[214:215], v[206:207] op_sel:[1,0,0]
	v_pk_fma_f32 v[208:209], v[150:151], v[216:217], v[208:209] op_sel:[1,0,0]
	v_cvt_pk_f32_fp8_e32 v[218:219], v7
	v_cvt_pk_f32_fp8_sdwa v[220:221], v7 src0_sel:WORD_1
	v_pk_fma_f32 v[210:211], v[150:151], v[218:219], v[210:211] op_sel:[1,0,0]
	v_pk_fma_f32 v[212:213], v[150:151], v[220:221], v[212:213] op_sel:[1,0,0]
	s_waitcnt vmcnt(29)
	v_cvt_pk_f32_fp8_e32 v[214:215], v8
	v_cvt_pk_f32_fp8_sdwa v[216:217], v8 src0_sel:WORD_1
	v_pk_fma_f32 v[198:199], v[152:153], v[214:215], v[198:199] op_sel_hi:[0,1,1]
	v_pk_fma_f32 v[200:201], v[152:153], v[216:217], v[200:201] op_sel_hi:[0,1,1]
	v_cvt_pk_f32_fp8_e32 v[218:219], v9
	v_cvt_pk_f32_fp8_sdwa v[220:221], v9 src0_sel:WORD_1
	v_pk_fma_f32 v[202:203], v[152:153], v[218:219], v[202:203] op_sel_hi:[0,1,1]
	v_pk_fma_f32 v[204:205], v[152:153], v[220:221], v[204:205] op_sel_hi:[0,1,1]
	v_cvt_pk_f32_fp8_e32 v[214:215], v10
	v_cvt_pk_f32_fp8_sdwa v[216:217], v10 src0_sel:WORD_1
	v_pk_fma_f32 v[206:207], v[152:153], v[214:215], v[206:207] op_sel_hi:[0,1,1]
	v_pk_fma_f32 v[208:209], v[152:153], v[216:217], v[208:209] op_sel_hi:[0,1,1]
	v_cvt_pk_f32_fp8_e32 v[218:219], v11
	v_cvt_pk_f32_fp8_sdwa v[220:221], v11 src0_sel:WORD_1
	v_pk_fma_f32 v[210:211], v[152:153], v[218:219], v[210:211] op_sel_hi:[0,1,1]
	v_pk_fma_f32 v[212:213], v[152:153], v[220:221], v[212:213] op_sel_hi:[0,1,1]
	s_waitcnt vmcnt(28)
	v_cvt_pk_f32_fp8_e32 v[214:215], v12
	v_cvt_pk_f32_fp8_sdwa v[216:217], v12 src0_sel:WORD_1
	v_pk_fma_f32 v[198:199], v[152:153], v[214:215], v[198:199] op_sel:[1,0,0]
	v_pk_fma_f32 v[200:201], v[152:153], v[216:217], v[200:201] op_sel:[1,0,0]
	v_cvt_pk_f32_fp8_e32 v[218:219], v13
	v_cvt_pk_f32_fp8_sdwa v[220:221], v13 src0_sel:WORD_1
	v_pk_fma_f32 v[202:203], v[152:153], v[218:219], v[202:203] op_sel:[1,0,0]
	v_pk_fma_f32 v[204:205], v[152:153], v[220:221], v[204:205] op_sel:[1,0,0]
	v_cvt_pk_f32_fp8_e32 v[214:215], v14
	v_cvt_pk_f32_fp8_sdwa v[216:217], v14 src0_sel:WORD_1
	v_pk_fma_f32 v[206:207], v[152:153], v[214:215], v[206:207] op_sel:[1,0,0]
	v_pk_fma_f32 v[208:209], v[152:153], v[216:217], v[208:209] op_sel:[1,0,0]
	v_cvt_pk_f32_fp8_e32 v[218:219], v15
	v_cvt_pk_f32_fp8_sdwa v[220:221], v15 src0_sel:WORD_1
	v_pk_fma_f32 v[210:211], v[152:153], v[218:219], v[210:211] op_sel:[1,0,0]
	v_pk_fma_f32 v[212:213], v[152:153], v[220:221], v[212:213] op_sel:[1,0,0]
	ds_read_b128 v[150:153], v139 offset:0
	s_waitcnt vmcnt(27)
; #define LAS __attribute__((address_space(3)))
; __device__ __forceinline__ void kv8_pv(const u32x4 (&buf)[8], f32x2v (&o2)[8], const LAS float* srow, int b) {
;     const LAS f32x4* p4 = (const LAS f32x4*)(srow + b * 8);
;     const f32x4 p0 = p4[0], p1 = p4[1];
;     const float p[8] = {p0.x, p0.y, p0.z, p0.w, p1.x, p1.y, p1.z, p1.w};
; #pragma unroll
;     for (int u = 0; u < 8; ++u) {
;         const u32x4 v = buf[u]; const f32x2v pp = {p[u], p[u]};
;         o2[0] = __builtin_elementwise_fma(pp, __builtin_amdgcn_cvt_pk_f32_fp8(v.x, false), o2[0]); o2[1] = __builtin_elementwise_fma(pp, __builtin_amdgcn_cvt_pk_f32_fp8(v.x, true), o2[1]);
;         o2[2] = __builtin_elementwise_fma(pp, __builtin_amdgcn_cvt_pk_f32_fp8(v.y, false), o2[2]); o2[3] = __builtin_elementwise_fma(pp, __builtin_amdgcn_cvt_pk_f32_fp8(v.y, true), o2[3]);
;         o2[4] = __builtin_elementwise_fma(pp, __builtin_amdgcn_cvt_pk_f32_fp8(v.z, false), o2[4]); o2[5] = __builtin_elementwise_fma(pp, __builtin_amdgcn_cvt_pk_f32_fp8(v.z, true), o2[5]);
;         o2[6] = __builtin_elementwise_fma(pp, __builtin_amdgcn_cvt_pk_f32_fp8(v.w, false), o2[6]); o2[7] = __builtin_elementwise_fma(pp, __builtin_amdgcn_cvt_pk_f32_fp8(v.w, true), o2[7]);
;     }
; __device__ __forceinline__ void attn_query8(const unsigned char* __restrict__ KV8, const bf16_t* __restrict__ Z, const int* __restrict__ SEL, bf16_t* __restrict__ YMIX, int t, LAS float* sbuf  ) {
;     ...
; #pragma unroll 1
;     for (int b = 0; b < nb; b += 3) {
;         kv8_issue(C, rs, lvo, 1024, iv, CLAMPB(b + 2));
;         kv8_pv(A, o, srow, b);
;         kv8_issue(A, rs, lvo, 1024, iv, CLAMPB(b + 3));
;         if (b + 1 < nb) kv8_pv(B, o, srow, b + 1);
;         kv8_issue(B, rs, lvo, 1024, iv, CLAMPB(b + 4));
;         if (b + 2 < nb) kv8_pv(C, o, srow, b + 2);
	v_cvt_pk_f32_fp8_e32 v[214:215], v16
	v_cvt_pk_f32_fp8_sdwa v[216:217], v16 src0_sel:WORD_1
	v_pk_fma_f32 v[198:199], v[154:155], v[214:215], v[198:199] op_sel_hi:[0,1,1]
	v_pk_fma_f32 v[200:201], v[154:155], v[216:217], v[200:201] op_sel_hi:[0,1,1]
	v_cvt_pk_f32_fp8_e32 v[218:219], v17
	v_cvt_pk_f32_fp8_sdwa v[220:221], v17 src0_sel:WORD_1
	v_pk_fma_f32 v[202:203], v[154:155], v[218:219], v[202:203] op_sel_hi:[0,1,1]
	v_pk_fma_f32 v[204:205], v[154:155], v[220:221], v[204:205] op_sel_hi:[0,1,1]
	v_cvt_pk_f32_fp8_e32 v[214:215], v18
	v_cvt_pk_f32_fp8_sdwa v[216:217], v18 src0_sel:WORD_1
	v_pk_fma_f32 v[206:207], v[154:155], v[214:215], v[206:207] op_sel_hi:[0,1,1]
	v_pk_fma_f32 v[208:209], v[154:155], v[216:217], v[208:209] op_sel_hi:[0,1,1]
	v_cvt_pk_f32_fp8_e32 v[218:219], v19
	v_cvt_pk_f32_fp8_sdwa v[220:221], v19 src0_sel:WORD_1
	v_pk_fma_f32 v[210:211], v[154:155], v[218:219], v[210:211] op_sel_hi:[0,1,1]
	v_pk_fma_f32 v[212:213], v[154:155], v[220:221], v[212:213] op_sel_hi:[0,1,1]
	s_waitcnt vmcnt(26)
	v_cvt_pk_f32_fp8_e32 v[214:215], v20
	v_cvt_pk_f32_fp8_sdwa v[216:217], v20 src0_sel:WORD_1
	v_pk_fma_f32 v[198:199], v[154:155], v[214:215], v[198:199] op_sel:[1,0,0]
	v_pk_fma_f32 v[200:201], v[154:155], v[216:217], v[200:201] op_sel:[1,0,0]
	v_cvt_pk_f32_fp8_e32 v[218:219], v21
	v_cvt_pk_f32_fp8_sdwa v[220:221], v21 src0_sel:WORD_1
	v_pk_fma_f32 v[202:203], v[154:155], v[218:219], v[202:203] op_sel:[1,0,0]
	v_pk_fma_f32 v[204:205], v[154:155], v[220:221], v[204:205] op_sel:[1,0,0]
	v_cvt_pk_f32_fp8_e32 v[214:215], v22
	v_cvt_pk_f32_fp8_sdwa v[216:217], v22 src0_sel:WORD_1
	v_pk_fma_f32 v[206:207], v[154:155], v[214:215], v[206:207] op_sel:[1,0,0]
	v_pk_fma_f32 v[208:209], v[154:155], v[216:217], v[208:209] op_sel:[1,0,0]
	v_cvt_pk_f32_fp8_e32 v[218:219], v23
	v_cvt_pk_f32_fp8_sdwa v[220:221], v23 src0_sel:WORD_1
	v_pk_fma_f32 v[210:211], v[154:155], v[218:219], v[210:211] op_sel:[1,0,0]
	v_pk_fma_f32 v[212:213], v[154:155], v[220:221], v[212:213] op_sel:[1,0,0]
	s_waitcnt lgkmcnt(0)
	v_lshl_add_u32 v150, v150, 8, v138
	v_lshl_add_u32 v151, v151, 8, v138
	v_lshl_add_u32 v152, v152, 8, v138
	v_lshl_add_u32 v153, v153, 8, v138
	buffer_load_dwordx4 v[0:3], v150, s[16:19], s26 offen sc0
	buffer_load_dwordx4 v[4:7], v151, s[16:19], s26 offen sc0
	buffer_load_dwordx4 v[8:11], v152, s[16:19], s26 offen sc0
	buffer_load_dwordx4 v[12:15], v153, s[16:19], s26 offen sc0
	s_waitcnt vmcnt(29)
	v_cvt_pk_f32_fp8_e32 v[214:215], v24
	v_cvt_pk_f32_fp8_sdwa v[216:217], v24 src0_sel:WORD_1
	v_pk_fma_f32 v[198:199], v[156:157], v[214:215], v[198:199] op_sel_hi:[0,1,1]
	v_pk_fma_f32 v[200:201], v[156:157], v[216:217], v[200:201] op_sel_hi:[0,1,1]
	v_cvt_pk_f32_fp8_e32 v[218:219], v25
	v_cvt_pk_f32_fp8_sdwa v[220:221], v25 src0_sel:WORD_1
	v_pk_fma_f32 v[202:203], v[156:157], v[218:219], v[202:203] op_sel_hi:[0,1,1]
	v_pk_fma_f32 v[204:205], v[156:157], v[220:221], v[204:205] op_sel_hi:[0,1,1]
	v_cvt_pk_f32_fp8_e32 v[214:215], v26
	v_cvt_pk_f32_fp8_sdwa v[216:217], v26 src0_sel:WORD_1
	v_pk_fma_f32 v[206:207], v[156:157], v[214:215], v[206:207] op_sel_hi:[0,1,1]
	v_pk_fma_f32 v[208:209], v[156:157], v[216:217], v[208:209] op_sel_hi:[0,1,1]
	v_cvt_pk_f32_fp8_e32 v[218:219], v27
	v_cvt_pk_f32_fp8_sdwa v[220:221], v27 src0_sel:WORD_1
	v_pk_fma_f32 v[210:211], v[156:157], v[218:219], v[210:211] op_sel_hi:[0,1,1]
	v_pk_fma_f32 v[212:213], v[156:157], v[220:221], v[212:213] op_sel_hi:[0,1,1]
	s_waitcnt vmcnt(28)
	v_cvt_pk_f32_fp8_e32 v[214:215], v28
	v_cvt_pk_f32_fp8_sdwa v[216:217], v28 src0_sel:WORD_1
	v_pk_fma_f32 v[198:199], v[156:157], v[214:215], v[198:199] op_sel:[1,0,0]
	v_pk_fma_f32 v[200:201], v[156:157], v[216:217], v[200:201] op_sel:[1,0,0]
	v_cvt_pk_f32_fp8_e32 v[218:219], v29
	v_cvt_pk_f32_fp8_sdwa v[220:221], v29 src0_sel:WORD_1
	v_pk_fma_f32 v[202:203], v[156:157], v[218:219], v[202:203] op_sel:[1,0,0]
	v_pk_fma_f32 v[204:205], v[156:157], v[220:221], v[204:205] op_sel:[1,0,0]
	v_cvt_pk_f32_fp8_e32 v[214:215], v30
	v_cvt_pk_f32_fp8_sdwa v[216:217], v30 src0_sel:WORD_1
	v_pk_fma_f32 v[206:207], v[156:157], v[214:215], v[206:207] op_sel:[1,0,0]
	v_pk_fma_f32 v[208:209], v[156:157], v[216:217], v[208:209] op_sel:[1,0,0]
	v_cvt_pk_f32_fp8_e32 v[218:219], v31
	v_cvt_pk_f32_fp8_sdwa v[220:221], v31 src0_sel:WORD_1
	v_pk_fma_f32 v[210:211], v[156:157], v[218:219], v[210:211] op_sel:[1,0,0]
	v_pk_fma_f32 v[212:213], v[156:157], v[220:221], v[212:213] op_sel:[1,0,0]
	ds_read_b128 v[154:157], v139 offset:16
	s_waitcnt vmcnt(27)
	v_cvt_pk_f32_fp8_e32 v[214:215], v32
	v_cvt_pk_f32_fp8_sdwa v[216:217], v32 src0_sel:WORD_1
	v_pk_fma_f32 v[198:199], v[158:159], v[214:215], v[198:199] op_sel_hi:[0,1,1]
	v_pk_fma_f32 v[200:201], v[158:159], v[216:217], v[200:201] op_sel_hi:[0,1,1]
	v_cvt_pk_f32_fp8_e32 v[218:219], v33
	v_cvt_pk_f32_fp8_sdwa v[220:221], v33 src0_sel:WORD_1
	v_pk_fma_f32 v[202:203], v[158:159], v[218:219], v[202:203] op_sel_hi:[0,1,1]
	v_pk_fma_f32 v[204:205], v[158:159], v[220:221], v[204:205] op_sel_hi:[0,1,1]
	v_cvt_pk_f32_fp8_e32 v[214:215], v34
	v_cvt_pk_f32_fp8_sdwa v[216:217], v34 src0_sel:WORD_1
	v_pk_fma_f32 v[206:207], v[158:159], v[214:215], v[206:207] op_sel_hi:[0,1,1]
	v_pk_fma_f32 v[208:209], v[158:159], v[216:217], v[208:209] op_sel_hi:[0,1,1]
	v_cvt_pk_f32_fp8_e32 v[218:219], v35
	v_cvt_pk_f32_fp8_sdwa v[220:221], v35 src0_sel:WORD_1
	v_pk_fma_f32 v[210:211], v[158:159], v[218:219], v[210:211] op_sel_hi:[0,1,1]
	v_pk_fma_f32 v[212:213], v[158:159], v[220:221], v[212:213] op_sel_hi:[0,1,1]
	s_waitcnt vmcnt(26)
; #define LAS __attribute__((address_space(3)))
; __device__ __forceinline__ void kv8_pv(const u32x4 (&buf)[8], f32x2v (&o2)[8], const LAS float* srow, int b) {
;     const LAS f32x4* p4 = (const LAS f32x4*)(srow + b * 8);
;     const f32x4 p0 = p4[0], p1 = p4[1];
;     const float p[8] = {p0.x, p0.y, p0.z, p0.w, p1.x, p1.y, p1.z, p1.w};
; #pragma unroll
;     for (int u = 0; u < 8; ++u) {
;         const u32x4 v = buf[u]; const f32x2v pp = {p[u], p[u]};
;         o2[0] = __builtin_elementwise_fma(pp, __builtin_amdgcn_cvt_pk_f32_fp8(v.x, false), o2[0]); o2[1] = __builtin_elementwise_fma(pp, __builtin_amdgcn_cvt_pk_f32_fp8(v.x, true), o2[1]);
;         o2[2] = __builtin_elementwise_fma(pp, __builtin_amdgcn_cvt_pk_f32_fp8(v.y, false), o2[2]); o2[3] = __builtin_elementwise_fma(pp, __builtin_amdgcn_cvt_pk_f32_fp8(v.y, true), o2[3]);
;         o2[4] = __builtin_elementwise_fma(pp, __builtin_amdgcn_cvt_pk_f32_fp8(v.z, false), o2[4]); o2[5] = __builtin_elementwise_fma(pp, __builtin_amdgcn_cvt_pk_f32_fp8(v.z, true), o2[5]);
;         o2[6] = __builtin_elementwise_fma(pp, __builtin_amdgcn_cvt_pk_f32_fp8(v.w, false), o2[6]); o2[7] = __builtin_elementwise_fma(pp, __builtin_amdgcn_cvt_pk_f32_fp8(v.w, true), o2[7]);
;     }
; __device__ __forceinline__ void attn_query8(const unsigned char* __restrict__ KV8, const bf16_t* __restrict__ Z, const int* __restrict__ SEL, bf16_t* __restrict__ YMIX, int t, LAS float* sbuf  ) {
;     ...
; #pragma unroll 1
;     for (int b = 0; b < nb; b += 3) {
;         kv8_issue(C, rs, lvo, 1024, iv, CLAMPB(b + 2));
;         kv8_pv(A, o, srow, b);
;         kv8_issue(A, rs, lvo, 1024, iv, CLAMPB(b + 3));
;         if (b + 1 < nb) kv8_pv(B, o, srow, b + 1);
;         kv8_issue(B, rs, lvo, 1024, iv, CLAMPB(b + 4));
;         if (b + 2 < nb) kv8_pv(C, o, srow, b + 2);
	v_cvt_pk_f32_fp8_e32 v[214:215], v36
	v_cvt_pk_f32_fp8_sdwa v[216:217], v36 src0_sel:WORD_1
	v_pk_fma_f32 v[198:199], v[158:159], v[214:215], v[198:199] op_sel:[1,0,0]
	v_pk_fma_f32 v[200:201], v[158:159], v[216:217], v[200:201] op_sel:[1,0,0]
	v_cvt_pk_f32_fp8_e32 v[218:219], v37
	v_cvt_pk_f32_fp8_sdwa v[220:221], v37 src0_sel:WORD_1
	v_pk_fma_f32 v[202:203], v[158:159], v[218:219], v[202:203] op_sel:[1,0,0]
	v_pk_fma_f32 v[204:205], v[158:159], v[220:221], v[204:205] op_sel:[1,0,0]
	v_cvt_pk_f32_fp8_e32 v[214:215], v38
	v_cvt_pk_f32_fp8_sdwa v[216:217], v38 src0_sel:WORD_1
	v_pk_fma_f32 v[206:207], v[158:159], v[214:215], v[206:207] op_sel:[1,0,0]
	v_pk_fma_f32 v[208:209], v[158:159], v[216:217], v[208:209] op_sel:[1,0,0]
	v_cvt_pk_f32_fp8_e32 v[218:219], v39
	v_cvt_pk_f32_fp8_sdwa v[220:221], v39 src0_sel:WORD_1
	v_pk_fma_f32 v[210:211], v[158:159], v[218:219], v[210:211] op_sel:[1,0,0]
	v_pk_fma_f32 v[212:213], v[158:159], v[220:221], v[212:213] op_sel:[1,0,0]
	s_waitcnt lgkmcnt(0)
	v_lshl_add_u32 v154, v154, 8, v138
	v_lshl_add_u32 v155, v155, 8, v138
	v_lshl_add_u32 v156, v156, 8, v138
	v_lshl_add_u32 v157, v157, 8, v138
	buffer_load_dwordx4 v[16:19], v154, s[16:19], s26 offen sc0
	buffer_load_dwordx4 v[20:23], v155, s[16:19], s26 offen sc0
	buffer_load_dwordx4 v[24:27], v156, s[16:19], s26 offen sc0
	buffer_load_dwordx4 v[28:31], v157, s[16:19], s26 offen sc0
	s_waitcnt vmcnt(29)
	v_cvt_pk_f32_fp8_e32 v[214:215], v40
	v_cvt_pk_f32_fp8_sdwa v[216:217], v40 src0_sel:WORD_1
	v_pk_fma_f32 v[198:199], v[160:161], v[214:215], v[198:199] op_sel_hi:[0,1,1]
	v_pk_fma_f32 v[200:201], v[160:161], v[216:217], v[200:201] op_sel_hi:[0,1,1]
	v_cvt_pk_f32_fp8_e32 v[218:219], v41
	v_cvt_pk_f32_fp8_sdwa v[220:221], v41 src0_sel:WORD_1
	v_pk_fma_f32 v[202:203], v[160:161], v[218:219], v[202:203] op_sel_hi:[0,1,1]
	v_pk_fma_f32 v[204:205], v[160:161], v[220:221], v[204:205] op_sel_hi:[0,1,1]
	v_cvt_pk_f32_fp8_e32 v[214:215], v42
	v_cvt_pk_f32_fp8_sdwa v[216:217], v42 src0_sel:WORD_1
	v_pk_fma_f32 v[206:207], v[160:161], v[214:215], v[206:207] op_sel_hi:[0,1,1]
	v_pk_fma_f32 v[208:209], v[160:161], v[216:217], v[208:209] op_sel_hi:[0,1,1]
	v_cvt_pk_f32_fp8_e32 v[218:219], v43
	v_cvt_pk_f32_fp8_sdwa v[220:221], v43 src0_sel:WORD_1
	v_pk_fma_f32 v[210:211], v[160:161], v[218:219], v[210:211] op_sel_hi:[0,1,1]
	v_pk_fma_f32 v[212:213], v[160:161], v[220:221], v[212:213] op_sel_hi:[0,1,1]
	s_waitcnt vmcnt(28)
	v_cvt_pk_f32_fp8_e32 v[214:215], v44
	v_cvt_pk_f32_fp8_sdwa v[216:217], v44 src0_sel:WORD_1
	v_pk_fma_f32 v[198:199], v[160:161], v[214:215], v[198:199] op_sel:[1,0,0]
	v_pk_fma_f32 v[200:201], v[160:161], v[216:217], v[200:201] op_sel:[1,0,0]
	v_cvt_pk_f32_fp8_e32 v[218:219], v45
	v_cvt_pk_f32_fp8_sdwa v[220:221], v45 src0_sel:WORD_1
	v_pk_fma_f32 v[202:203], v[160:161], v[218:219], v[202:203] op_sel:[1,0,0]
	v_pk_fma_f32 v[204:205], v[160:161], v[220:221], v[204:205] op_sel:[1,0,0]
	v_cvt_pk_f32_fp8_e32 v[214:215], v46
	v_cvt_pk_f32_fp8_sdwa v[216:217], v46 src0_sel:WORD_1
	v_pk_fma_f32 v[206:207], v[160:161], v[214:215], v[206:207] op_sel:[1,0,0]
	v_pk_fma_f32 v[208:209], v[160:161], v[216:217], v[208:209] op_sel:[1,0,0]
	v_cvt_pk_f32_fp8_e32 v[218:219], v47
	v_cvt_pk_f32_fp8_sdwa v[220:221], v47 src0_sel:WORD_1
	v_pk_fma_f32 v[210:211], v[160:161], v[218:219], v[210:211] op_sel:[1,0,0]
	v_pk_fma_f32 v[212:213], v[160:161], v[220:221], v[212:213] op_sel:[1,0,0]
	ds_read_b128 v[158:161], v139 offset:32
	s_waitcnt vmcnt(27)
	v_cvt_pk_f32_fp8_e32 v[214:215], v48
	v_cvt_pk_f32_fp8_sdwa v[216:217], v48 src0_sel:WORD_1
	v_pk_fma_f32 v[198:199], v[162:163], v[214:215], v[198:199] op_sel_hi:[0,1,1]
	v_pk_fma_f32 v[200:201], v[162:163], v[216:217], v[200:201] op_sel_hi:[0,1,1]
	v_cvt_pk_f32_fp8_e32 v[218:219], v49
	v_cvt_pk_f32_fp8_sdwa v[220:221], v49 src0_sel:WORD_1
	v_pk_fma_f32 v[202:203], v[162:163], v[218:219], v[202:203] op_sel_hi:[0,1,1]
	v_pk_fma_f32 v[204:205], v[162:163], v[220:221], v[204:205] op_sel_hi:[0,1,1]
	v_cvt_pk_f32_fp8_e32 v[214:215], v50
	v_cvt_pk_f32_fp8_sdwa v[216:217], v50 src0_sel:WORD_1
	v_pk_fma_f32 v[206:207], v[162:163], v[214:215], v[206:207] op_sel_hi:[0,1,1]
	v_pk_fma_f32 v[208:209], v[162:163], v[216:217], v[208:209] op_sel_hi:[0,1,1]
	v_cvt_pk_f32_fp8_e32 v[218:219], v51
	v_cvt_pk_f32_fp8_sdwa v[220:221], v51 src0_sel:WORD_1
	v_pk_fma_f32 v[210:211], v[162:163], v[218:219], v[210:211] op_sel_hi:[0,1,1]
	v_pk_fma_f32 v[212:213], v[162:163], v[220:221], v[212:213] op_sel_hi:[0,1,1]
	s_waitcnt vmcnt(26)
	v_cvt_pk_f32_fp8_e32 v[214:215], v52
	v_cvt_pk_f32_fp8_sdwa v[216:217], v52 src0_sel:WORD_1
	v_pk_fma_f32 v[198:199], v[162:163], v[214:215], v[198:199] op_sel:[1,0,0]
	v_pk_fma_f32 v[200:201], v[162:163], v[216:217], v[200:201] op_sel:[1,0,0]
	v_cvt_pk_f32_fp8_e32 v[218:219], v53
	v_cvt_pk_f32_fp8_sdwa v[220:221], v53 src0_sel:WORD_1
	v_pk_fma_f32 v[202:203], v[162:163], v[218:219], v[202:203] op_sel:[1,0,0]
	v_pk_fma_f32 v[204:205], v[162:163], v[220:221], v[204:205] op_sel:[1,0,0]
	v_cvt_pk_f32_fp8_e32 v[214:215], v54
	v_cvt_pk_f32_fp8_sdwa v[216:217], v54 src0_sel:WORD_1
	v_pk_fma_f32 v[206:207], v[162:163], v[214:215], v[206:207] op_sel:[1,0,0]
	v_pk_fma_f32 v[208:209], v[162:163], v[216:217], v[208:209] op_sel:[1,0,0]
	v_cvt_pk_f32_fp8_e32 v[218:219], v55
	v_cvt_pk_f32_fp8_sdwa v[220:221], v55 src0_sel:WORD_1
	v_pk_fma_f32 v[210:211], v[162:163], v[218:219], v[210:211] op_sel:[1,0,0]
	v_pk_fma_f32 v[212:213], v[162:163], v[220:221], v[212:213] op_sel:[1,0,0]
	s_waitcnt lgkmcnt(0)
; #define LAS __attribute__((address_space(3)))
; __device__ __forceinline__ void kv8_pv(const u32x4 (&buf)[8], f32x2v (&o2)[8], const LAS float* srow, int b) {
;     const LAS f32x4* p4 = (const LAS f32x4*)(srow + b * 8);
;     const f32x4 p0 = p4[0], p1 = p4[1];
;     const float p[8] = {p0.x, p0.y, p0.z, p0.w, p1.x, p1.y, p1.z, p1.w};
; #pragma unroll
;     for (int u = 0; u < 8; ++u) {
;         const u32x4 v = buf[u]; const f32x2v pp = {p[u], p[u]};
;         o2[0] = __builtin_elementwise_fma(pp, __builtin_amdgcn_cvt_pk_f32_fp8(v.x, false), o2[0]); o2[1] = __builtin_elementwise_fma(pp, __builtin_amdgcn_cvt_pk_f32_fp8(v.x, true), o2[1]);
;         o2[2] = __builtin_elementwise_fma(pp, __builtin_amdgcn_cvt_pk_f32_fp8(v.y, false), o2[2]); o2[3] = __builtin_elementwise_fma(pp, __builtin_amdgcn_cvt_pk_f32_fp8(v.y, true), o2[3]);
;         o2[4] = __builtin_elementwise_fma(pp, __builtin_amdgcn_cvt_pk_f32_fp8(v.z, false), o2[4]); o2[5] = __builtin_elementwise_fma(pp, __builtin_amdgcn_cvt_pk_f32_fp8(v.z, true), o2[5]);
;         o2[6] = __builtin_elementwise_fma(pp, __builtin_amdgcn_cvt_pk_f32_fp8(v.w, false), o2[6]); o2[7] = __builtin_elementwise_fma(pp, __builtin_amdgcn_cvt_pk_f32_fp8(v.w, true), o2[7]);
;     }
; __device__ __forceinline__ void attn_query8(const unsigned char* __restrict__ KV8, const bf16_t* __restrict__ Z, const int* __restrict__ SEL, bf16_t* __restrict__ YMIX, int t, LAS float* sbuf  ) {
;     ...
; #pragma unroll 1
;     for (int b = 0; b < nb; b += 3) {
;         kv8_issue(C, rs, lvo, 1024, iv, CLAMPB(b + 2));
;         kv8_pv(A, o, srow, b);
;         kv8_issue(A, rs, lvo, 1024, iv, CLAMPB(b + 3));
;         if (b + 1 < nb) kv8_pv(B, o, srow, b + 1);
;         kv8_issue(B, rs, lvo, 1024, iv, CLAMPB(b + 4));
;         if (b + 2 < nb) kv8_pv(C, o, srow, b + 2);
	v_lshl_add_u32 v158, v158, 8, v138
	v_lshl_add_u32 v159, v159, 8, v138
	v_lshl_add_u32 v160, v160, 8, v138
	v_lshl_add_u32 v161, v161, 8, v138
	buffer_load_dwordx4 v[32:35], v158, s[16:19], s26 offen sc0
	buffer_load_dwordx4 v[36:39], v159, s[16:19], s26 offen sc0
	buffer_load_dwordx4 v[40:43], v160, s[16:19], s26 offen sc0
	buffer_load_dwordx4 v[44:47], v161, s[16:19], s26 offen sc0
	s_waitcnt vmcnt(29)
	v_cvt_pk_f32_fp8_e32 v[214:215], v56
	v_cvt_pk_f32_fp8_sdwa v[216:217], v56 src0_sel:WORD_1
	v_pk_fma_f32 v[198:199], v[164:165], v[214:215], v[198:199] op_sel_hi:[0,1,1]
	v_pk_fma_f32 v[200:201], v[164:165], v[216:217], v[200:201] op_sel_hi:[0,1,1]
	v_cvt_pk_f32_fp8_e32 v[218:219], v57
	v_cvt_pk_f32_fp8_sdwa v[220:221], v57 src0_sel:WORD_1
	v_pk_fma_f32 v[202:203], v[164:165], v[218:219], v[202:203] op_sel_hi:[0,1,1]
	v_pk_fma_f32 v[204:205], v[164:165], v[220:221], v[204:205] op_sel_hi:[0,1,1]
	v_cvt_pk_f32_fp8_e32 v[214:215], v58
	v_cvt_pk_f32_fp8_sdwa v[216:217], v58 src0_sel:WORD_1
	v_pk_fma_f32 v[206:207], v[164:165], v[214:215], v[206:207] op_sel_hi:[0,1,1]
	v_pk_fma_f32 v[208:209], v[164:165], v[216:217], v[208:209] op_sel_hi:[0,1,1]
	v_cvt_pk_f32_fp8_e32 v[218:219], v59
	v_cvt_pk_f32_fp8_sdwa v[220:221], v59 src0_sel:WORD_1
	v_pk_fma_f32 v[210:211], v[164:165], v[218:219], v[210:211] op_sel_hi:[0,1,1]
	v_pk_fma_f32 v[212:213], v[164:165], v[220:221], v[212:213] op_sel_hi:[0,1,1]
	s_waitcnt vmcnt(28)
	v_cvt_pk_f32_fp8_e32 v[214:215], v60
	v_cvt_pk_f32_fp8_sdwa v[216:217], v60 src0_sel:WORD_1
	v_pk_fma_f32 v[198:199], v[164:165], v[214:215], v[198:199] op_sel:[1,0,0]
	v_pk_fma_f32 v[200:201], v[164:165], v[216:217], v[200:201] op_sel:[1,0,0]
	v_cvt_pk_f32_fp8_e32 v[218:219], v61
	v_cvt_pk_f32_fp8_sdwa v[220:221], v61 src0_sel:WORD_1
	v_pk_fma_f32 v[202:203], v[164:165], v[218:219], v[202:203] op_sel:[1,0,0]
	v_pk_fma_f32 v[204:205], v[164:165], v[220:221], v[204:205] op_sel:[1,0,0]
	v_cvt_pk_f32_fp8_e32 v[214:215], v62
	v_cvt_pk_f32_fp8_sdwa v[216:217], v62 src0_sel:WORD_1
	v_pk_fma_f32 v[206:207], v[164:165], v[214:215], v[206:207] op_sel:[1,0,0]
	v_pk_fma_f32 v[208:209], v[164:165], v[216:217], v[208:209] op_sel:[1,0,0]
	v_cvt_pk_f32_fp8_e32 v[218:219], v63
	v_cvt_pk_f32_fp8_sdwa v[220:221], v63 src0_sel:WORD_1
	v_pk_fma_f32 v[210:211], v[164:165], v[218:219], v[210:211] op_sel:[1,0,0]
	v_pk_fma_f32 v[212:213], v[164:165], v[220:221], v[212:213] op_sel:[1,0,0]
	ds_read_b128 v[162:165], v139 offset:48
	s_waitcnt vmcnt(27)
	v_cvt_pk_f32_fp8_e32 v[214:215], v64
	v_cvt_pk_f32_fp8_sdwa v[216:217], v64 src0_sel:WORD_1
	v_pk_fma_f32 v[198:199], v[166:167], v[214:215], v[198:199] op_sel_hi:[0,1,1]
	v_pk_fma_f32 v[200:201], v[166:167], v[216:217], v[200:201] op_sel_hi:[0,1,1]
	v_cvt_pk_f32_fp8_e32 v[218:219], v65
	v_cvt_pk_f32_fp8_sdwa v[220:221], v65 src0_sel:WORD_1
	v_pk_fma_f32 v[202:203], v[166:167], v[218:219], v[202:203] op_sel_hi:[0,1,1]
	v_pk_fma_f32 v[204:205], v[166:167], v[220:221], v[204:205] op_sel_hi:[0,1,1]
	v_cvt_pk_f32_fp8_e32 v[214:215], v66
	v_cvt_pk_f32_fp8_sdwa v[216:217], v66 src0_sel:WORD_1
	v_pk_fma_f32 v[206:207], v[166:167], v[214:215], v[206:207] op_sel_hi:[0,1,1]
	v_pk_fma_f32 v[208:209], v[166:167], v[216:217], v[208:209] op_sel_hi:[0,1,1]
	v_cvt_pk_f32_fp8_e32 v[218:219], v67
	v_cvt_pk_f32_fp8_sdwa v[220:221], v67 src0_sel:WORD_1
	v_pk_fma_f32 v[210:211], v[166:167], v[218:219], v[210:211] op_sel_hi:[0,1,1]
	v_pk_fma_f32 v[212:213], v[166:167], v[220:221], v[212:213] op_sel_hi:[0,1,1]
	s_waitcnt vmcnt(26)
	v_cvt_pk_f32_fp8_e32 v[214:215], v68
	v_cvt_pk_f32_fp8_sdwa v[216:217], v68 src0_sel:WORD_1
	v_pk_fma_f32 v[198:199], v[166:167], v[214:215], v[198:199] op_sel:[1,0,0]
	v_pk_fma_f32 v[200:201], v[166:167], v[216:217], v[200:201] op_sel:[1,0,0]
	v_cvt_pk_f32_fp8_e32 v[218:219], v69
	v_cvt_pk_f32_fp8_sdwa v[220:221], v69 src0_sel:WORD_1
	v_pk_fma_f32 v[202:203], v[166:167], v[218:219], v[202:203] op_sel:[1,0,0]
	v_pk_fma_f32 v[204:205], v[166:167], v[220:221], v[204:205] op_sel:[1,0,0]
	v_cvt_pk_f32_fp8_e32 v[214:215], v70
	v_cvt_pk_f32_fp8_sdwa v[216:217], v70 src0_sel:WORD_1
	v_pk_fma_f32 v[206:207], v[166:167], v[214:215], v[206:207] op_sel:[1,0,0]
	v_pk_fma_f32 v[208:209], v[166:167], v[216:217], v[208:209] op_sel:[1,0,0]
	v_cvt_pk_f32_fp8_e32 v[218:219], v71
	v_cvt_pk_f32_fp8_sdwa v[220:221], v71 src0_sel:WORD_1
	v_pk_fma_f32 v[210:211], v[166:167], v[218:219], v[210:211] op_sel:[1,0,0]
	v_pk_fma_f32 v[212:213], v[166:167], v[220:221], v[212:213] op_sel:[1,0,0]
	s_waitcnt lgkmcnt(0)
	v_lshl_add_u32 v162, v162, 8, v138
	v_lshl_add_u32 v163, v163, 8, v138
	v_lshl_add_u32 v164, v164, 8, v138
	v_lshl_add_u32 v165, v165, 8, v138
	buffer_load_dwordx4 v[48:51], v162, s[16:19], s26 offen sc0
	buffer_load_dwordx4 v[52:55], v163, s[16:19], s26 offen sc0
	buffer_load_dwordx4 v[56:59], v164, s[16:19], s26 offen sc0
	buffer_load_dwordx4 v[60:63], v165, s[16:19], s26 offen sc0
	s_waitcnt vmcnt(29)
	v_cvt_pk_f32_fp8_e32 v[214:215], v72
	v_cvt_pk_f32_fp8_sdwa v[216:217], v72 src0_sel:WORD_1
	v_pk_fma_f32 v[198:199], v[168:169], v[214:215], v[198:199] op_sel_hi:[0,1,1]
	v_pk_fma_f32 v[200:201], v[168:169], v[216:217], v[200:201] op_sel_hi:[0,1,1]
	v_cvt_pk_f32_fp8_e32 v[218:219], v73
	v_cvt_pk_f32_fp8_sdwa v[220:221], v73 src0_sel:WORD_1
	v_pk_fma_f32 v[202:203], v[168:169], v[218:219], v[202:203] op_sel_hi:[0,1,1]
	v_pk_fma_f32 v[204:205], v[168:169], v[220:221], v[204:205] op_sel_hi:[0,1,1]
	v_cvt_pk_f32_fp8_e32 v[214:215], v74
	v_cvt_pk_f32_fp8_sdwa v[216:217], v74 src0_sel:WORD_1
	v_pk_fma_f32 v[206:207], v[168:169], v[214:215], v[206:207] op_sel_hi:[0,1,1]
	v_pk_fma_f32 v[208:209], v[168:169], v[216:217], v[208:209] op_sel_hi:[0,1,1]
	v_cvt_pk_f32_fp8_e32 v[218:219], v75
	v_cvt_pk_f32_fp8_sdwa v[220:221], v75 src0_sel:WORD_1
	v_pk_fma_f32 v[210:211], v[168:169], v[218:219], v[210:211] op_sel_hi:[0,1,1]
	v_pk_fma_f32 v[212:213], v[168:169], v[220:221], v[212:213] op_sel_hi:[0,1,1]
	s_waitcnt vmcnt(28)
; #define LAS __attribute__((address_space(3)))
; __device__ __forceinline__ void kv8_pv(const u32x4 (&buf)[8], f32x2v (&o2)[8], const LAS float* srow, int b) {
;     const LAS f32x4* p4 = (const LAS f32x4*)(srow + b * 8);
;     const f32x4 p0 = p4[0], p1 = p4[1];
;     const float p[8] = {p0.x, p0.y, p0.z, p0.w, p1.x, p1.y, p1.z, p1.w};
; #pragma unroll
;     for (int u = 0; u < 8; ++u) {
;         const u32x4 v = buf[u]; const f32x2v pp = {p[u], p[u]};
;         o2[0] = __builtin_elementwise_fma(pp, __builtin_amdgcn_cvt_pk_f32_fp8(v.x, false), o2[0]); o2[1] = __builtin_elementwise_fma(pp, __builtin_amdgcn_cvt_pk_f32_fp8(v.x, true), o2[1]);
;         o2[2] = __builtin_elementwise_fma(pp, __builtin_amdgcn_cvt_pk_f32_fp8(v.y, false), o2[2]); o2[3] = __builtin_elementwise_fma(pp, __builtin_amdgcn_cvt_pk_f32_fp8(v.y, true), o2[3]);
;         o2[4] = __builtin_elementwise_fma(pp, __builtin_amdgcn_cvt_pk_f32_fp8(v.z, false), o2[4]); o2[5] = __builtin_elementwise_fma(pp, __builtin_amdgcn_cvt_pk_f32_fp8(v.z, true), o2[5]);
;         o2[6] = __builtin_elementwise_fma(pp, __builtin_amdgcn_cvt_pk_f32_fp8(v.w, false), o2[6]); o2[7] = __builtin_elementwise_fma(pp, __builtin_amdgcn_cvt_pk_f32_fp8(v.w, true), o2[7]);
;     }
; __device__ __forceinline__ void attn_query8(const unsigned char* __restrict__ KV8, const bf16_t* __restrict__ Z, const int* __restrict__ SEL, bf16_t* __restrict__ YMIX, int t, LAS float* sbuf  ) {
;     ...
; #pragma unroll 1
;     for (int b = 0; b < nb; b += 3) {
;         kv8_issue(C, rs, lvo, 1024, iv, CLAMPB(b + 2));
;         kv8_pv(A, o, srow, b);
;         kv8_issue(A, rs, lvo, 1024, iv, CLAMPB(b + 3));
;         if (b + 1 < nb) kv8_pv(B, o, srow, b + 1);
;         kv8_issue(B, rs, lvo, 1024, iv, CLAMPB(b + 4));
;         if (b + 2 < nb) kv8_pv(C, o, srow, b + 2);
	v_cvt_pk_f32_fp8_e32 v[214:215], v76
	v_cvt_pk_f32_fp8_sdwa v[216:217], v76 src0_sel:WORD_1
	v_pk_fma_f32 v[198:199], v[168:169], v[214:215], v[198:199] op_sel:[1,0,0]
	v_pk_fma_f32 v[200:201], v[168:169], v[216:217], v[200:201] op_sel:[1,0,0]
	v_cvt_pk_f32_fp8_e32 v[218:219], v77
	v_cvt_pk_f32_fp8_sdwa v[220:221], v77 src0_sel:WORD_1
	v_pk_fma_f32 v[202:203], v[168:169], v[218:219], v[202:203] op_sel:[1,0,0]
	v_pk_fma_f32 v[204:205], v[168:169], v[220:221], v[204:205] op_sel:[1,0,0]
	v_cvt_pk_f32_fp8_e32 v[214:215], v78
	v_cvt_pk_f32_fp8_sdwa v[216:217], v78 src0_sel:WORD_1
	v_pk_fma_f32 v[206:207], v[168:169], v[214:215], v[206:207] op_sel:[1,0,0]
	v_pk_fma_f32 v[208:209], v[168:169], v[216:217], v[208:209] op_sel:[1,0,0]
	v_cvt_pk_f32_fp8_e32 v[218:219], v79
	v_cvt_pk_f32_fp8_sdwa v[220:221], v79 src0_sel:WORD_1
	v_pk_fma_f32 v[210:211], v[168:169], v[218:219], v[210:211] op_sel:[1,0,0]
	v_pk_fma_f32 v[212:213], v[168:169], v[220:221], v[212:213] op_sel:[1,0,0]
	ds_read_b128 v[166:169], v139 offset:64
	s_waitcnt vmcnt(27)
	v_cvt_pk_f32_fp8_e32 v[214:215], v80
	v_cvt_pk_f32_fp8_sdwa v[216:217], v80 src0_sel:WORD_1
	v_pk_fma_f32 v[198:199], v[170:171], v[214:215], v[198:199] op_sel_hi:[0,1,1]
	v_pk_fma_f32 v[200:201], v[170:171], v[216:217], v[200:201] op_sel_hi:[0,1,1]
	v_cvt_pk_f32_fp8_e32 v[218:219], v81
	v_cvt_pk_f32_fp8_sdwa v[220:221], v81 src0_sel:WORD_1
	v_pk_fma_f32 v[202:203], v[170:171], v[218:219], v[202:203] op_sel_hi:[0,1,1]
	v_pk_fma_f32 v[204:205], v[170:171], v[220:221], v[204:205] op_sel_hi:[0,1,1]
	v_cvt_pk_f32_fp8_e32 v[214:215], v82
	v_cvt_pk_f32_fp8_sdwa v[216:217], v82 src0_sel:WORD_1
	v_pk_fma_f32 v[206:207], v[170:171], v[214:215], v[206:207] op_sel_hi:[0,1,1]
	v_pk_fma_f32 v[208:209], v[170:171], v[216:217], v[208:209] op_sel_hi:[0,1,1]
	v_cvt_pk_f32_fp8_e32 v[218:219], v83
	v_cvt_pk_f32_fp8_sdwa v[220:221], v83 src0_sel:WORD_1
	v_pk_fma_f32 v[210:211], v[170:171], v[218:219], v[210:211] op_sel_hi:[0,1,1]
	v_pk_fma_f32 v[212:213], v[170:171], v[220:221], v[212:213] op_sel_hi:[0,1,1]
	s_waitcnt vmcnt(26)
	v_cvt_pk_f32_fp8_e32 v[214:215], v84
	v_cvt_pk_f32_fp8_sdwa v[216:217], v84 src0_sel:WORD_1
	v_pk_fma_f32 v[198:199], v[170:171], v[214:215], v[198:199] op_sel:[1,0,0]
	v_pk_fma_f32 v[200:201], v[170:171], v[216:217], v[200:201] op_sel:[1,0,0]
	v_cvt_pk_f32_fp8_e32 v[218:219], v85
	v_cvt_pk_f32_fp8_sdwa v[220:221], v85 src0_sel:WORD_1
	v_pk_fma_f32 v[202:203], v[170:171], v[218:219], v[202:203] op_sel:[1,0,0]
	v_pk_fma_f32 v[204:205], v[170:171], v[220:221], v[204:205] op_sel:[1,0,0]
	v_cvt_pk_f32_fp8_e32 v[214:215], v86
	v_cvt_pk_f32_fp8_sdwa v[216:217], v86 src0_sel:WORD_1
	v_pk_fma_f32 v[206:207], v[170:171], v[214:215], v[206:207] op_sel:[1,0,0]
	v_pk_fma_f32 v[208:209], v[170:171], v[216:217], v[208:209] op_sel:[1,0,0]
	v_cvt_pk_f32_fp8_e32 v[218:219], v87
	v_cvt_pk_f32_fp8_sdwa v[220:221], v87 src0_sel:WORD_1
	v_pk_fma_f32 v[210:211], v[170:171], v[218:219], v[210:211] op_sel:[1,0,0]
	v_pk_fma_f32 v[212:213], v[170:171], v[220:221], v[212:213] op_sel:[1,0,0]
	s_waitcnt lgkmcnt(0)
	v_lshl_add_u32 v166, v166, 8, v138
	v_lshl_add_u32 v167, v167, 8, v138
	v_lshl_add_u32 v168, v168, 8, v138
	v_lshl_add_u32 v169, v169, 8, v138
	buffer_load_dwordx4 v[64:67], v166, s[16:19], s26 offen sc0
	buffer_load_dwordx4 v[68:71], v167, s[16:19], s26 offen sc0
	buffer_load_dwordx4 v[72:75], v168, s[16:19], s26 offen sc0
	buffer_load_dwordx4 v[76:79], v169, s[16:19], s26 offen sc0
	s_waitcnt vmcnt(29)
	v_cvt_pk_f32_fp8_e32 v[214:215], v88
	v_cvt_pk_f32_fp8_sdwa v[216:217], v88 src0_sel:WORD_1
	v_pk_fma_f32 v[198:199], v[172:173], v[214:215], v[198:199] op_sel_hi:[0,1,1]
	v_pk_fma_f32 v[200:201], v[172:173], v[216:217], v[200:201] op_sel_hi:[0,1,1]
	v_cvt_pk_f32_fp8_e32 v[218:219], v89
	v_cvt_pk_f32_fp8_sdwa v[220:221], v89 src0_sel:WORD_1
	v_pk_fma_f32 v[202:203], v[172:173], v[218:219], v[202:203] op_sel_hi:[0,1,1]
	v_pk_fma_f32 v[204:205], v[172:173], v[220:221], v[204:205] op_sel_hi:[0,1,1]
	v_cvt_pk_f32_fp8_e32 v[214:215], v90
	v_cvt_pk_f32_fp8_sdwa v[216:217], v90 src0_sel:WORD_1
	v_pk_fma_f32 v[206:207], v[172:173], v[214:215], v[206:207] op_sel_hi:[0,1,1]
	v_pk_fma_f32 v[208:209], v[172:173], v[216:217], v[208:209] op_sel_hi:[0,1,1]
	v_cvt_pk_f32_fp8_e32 v[218:219], v91
	v_cvt_pk_f32_fp8_sdwa v[220:221], v91 src0_sel:WORD_1
	v_pk_fma_f32 v[210:211], v[172:173], v[218:219], v[210:211] op_sel_hi:[0,1,1]
	v_pk_fma_f32 v[212:213], v[172:173], v[220:221], v[212:213] op_sel_hi:[0,1,1]
	s_waitcnt vmcnt(28)
	v_cvt_pk_f32_fp8_e32 v[214:215], v92
	v_cvt_pk_f32_fp8_sdwa v[216:217], v92 src0_sel:WORD_1
	v_pk_fma_f32 v[198:199], v[172:173], v[214:215], v[198:199] op_sel:[1,0,0]
	v_pk_fma_f32 v[200:201], v[172:173], v[216:217], v[200:201] op_sel:[1,0,0]
	v_cvt_pk_f32_fp8_e32 v[218:219], v93
	v_cvt_pk_f32_fp8_sdwa v[220:221], v93 src0_sel:WORD_1
	v_pk_fma_f32 v[202:203], v[172:173], v[218:219], v[202:203] op_sel:[1,0,0]
	v_pk_fma_f32 v[204:205], v[172:173], v[220:221], v[204:205] op_sel:[1,0,0]
	v_cvt_pk_f32_fp8_e32 v[214:215], v94
	v_cvt_pk_f32_fp8_sdwa v[216:217], v94 src0_sel:WORD_1
	v_pk_fma_f32 v[206:207], v[172:173], v[214:215], v[206:207] op_sel:[1,0,0]
	v_pk_fma_f32 v[208:209], v[172:173], v[216:217], v[208:209] op_sel:[1,0,0]
	v_cvt_pk_f32_fp8_e32 v[218:219], v95
	v_cvt_pk_f32_fp8_sdwa v[220:221], v95 src0_sel:WORD_1
	v_pk_fma_f32 v[210:211], v[172:173], v[218:219], v[210:211] op_sel:[1,0,0]
	v_pk_fma_f32 v[212:213], v[172:173], v[220:221], v[212:213] op_sel:[1,0,0]
	ds_read_b128 v[170:173], v139 offset:80
	s_waitcnt vmcnt(27)
; #define LAS __attribute__((address_space(3)))
; __device__ __forceinline__ void kv8_pv(const u32x4 (&buf)[8], f32x2v (&o2)[8], const LAS float* srow, int b) {
;     const LAS f32x4* p4 = (const LAS f32x4*)(srow + b * 8);
;     const f32x4 p0 = p4[0], p1 = p4[1];
;     const float p[8] = {p0.x, p0.y, p0.z, p0.w, p1.x, p1.y, p1.z, p1.w};
; #pragma unroll
;     for (int u = 0; u < 8; ++u) {
;         const u32x4 v = buf[u]; const f32x2v pp = {p[u], p[u]};
;         o2[0] = __builtin_elementwise_fma(pp, __builtin_amdgcn_cvt_pk_f32_fp8(v.x, false), o2[0]); o2[1] = __builtin_elementwise_fma(pp, __builtin_amdgcn_cvt_pk_f32_fp8(v.x, true), o2[1]);
;         o2[2] = __builtin_elementwise_fma(pp, __builtin_amdgcn_cvt_pk_f32_fp8(v.y, false), o2[2]); o2[3] = __builtin_elementwise_fma(pp, __builtin_amdgcn_cvt_pk_f32_fp8(v.y, true), o2[3]);
;         o2[4] = __builtin_elementwise_fma(pp, __builtin_amdgcn_cvt_pk_f32_fp8(v.z, false), o2[4]); o2[5] = __builtin_elementwise_fma(pp, __builtin_amdgcn_cvt_pk_f32_fp8(v.z, true), o2[5]);
;         o2[6] = __builtin_elementwise_fma(pp, __builtin_amdgcn_cvt_pk_f32_fp8(v.w, false), o2[6]); o2[7] = __builtin_elementwise_fma(pp, __builtin_amdgcn_cvt_pk_f32_fp8(v.w, true), o2[7]);
;     }
; __device__ __forceinline__ void attn_query8(const unsigned char* __restrict__ KV8, const bf16_t* __restrict__ Z, const int* __restrict__ SEL, bf16_t* __restrict__ YMIX, int t, LAS float* sbuf  ) {
;     ...
; #pragma unroll 1
;     for (int b = 0; b < nb; b += 3) {
;         kv8_issue(C, rs, lvo, 1024, iv, CLAMPB(b + 2));
;         kv8_pv(A, o, srow, b);
;         kv8_issue(A, rs, lvo, 1024, iv, CLAMPB(b + 3));
;         if (b + 1 < nb) kv8_pv(B, o, srow, b + 1);
;         kv8_issue(B, rs, lvo, 1024, iv, CLAMPB(b + 4));
;         if (b + 2 < nb) kv8_pv(C, o, srow, b + 2);
	v_cvt_pk_f32_fp8_e32 v[214:215], v96
	v_cvt_pk_f32_fp8_sdwa v[216:217], v96 src0_sel:WORD_1
	v_pk_fma_f32 v[198:199], v[174:175], v[214:215], v[198:199] op_sel_hi:[0,1,1]
	v_pk_fma_f32 v[200:201], v[174:175], v[216:217], v[200:201] op_sel_hi:[0,1,1]
	v_cvt_pk_f32_fp8_e32 v[218:219], v97
	v_cvt_pk_f32_fp8_sdwa v[220:221], v97 src0_sel:WORD_1
	v_pk_fma_f32 v[202:203], v[174:175], v[218:219], v[202:203] op_sel_hi:[0,1,1]
	v_pk_fma_f32 v[204:205], v[174:175], v[220:221], v[204:205] op_sel_hi:[0,1,1]
	v_cvt_pk_f32_fp8_e32 v[214:215], v98
	v_cvt_pk_f32_fp8_sdwa v[216:217], v98 src0_sel:WORD_1
	v_pk_fma_f32 v[206:207], v[174:175], v[214:215], v[206:207] op_sel_hi:[0,1,1]
	v_pk_fma_f32 v[208:209], v[174:175], v[216:217], v[208:209] op_sel_hi:[0,1,1]
	v_cvt_pk_f32_fp8_e32 v[218:219], v99
	v_cvt_pk_f32_fp8_sdwa v[220:221], v99 src0_sel:WORD_1
	v_pk_fma_f32 v[210:211], v[174:175], v[218:219], v[210:211] op_sel_hi:[0,1,1]
	v_pk_fma_f32 v[212:213], v[174:175], v[220:221], v[212:213] op_sel_hi:[0,1,1]
	s_waitcnt vmcnt(26)
	v_cvt_pk_f32_fp8_e32 v[214:215], v100
	v_cvt_pk_f32_fp8_sdwa v[216:217], v100 src0_sel:WORD_1
	v_pk_fma_f32 v[198:199], v[174:175], v[214:215], v[198:199] op_sel:[1,0,0]
	v_pk_fma_f32 v[200:201], v[174:175], v[216:217], v[200:201] op_sel:[1,0,0]
	v_cvt_pk_f32_fp8_e32 v[218:219], v101
	v_cvt_pk_f32_fp8_sdwa v[220:221], v101 src0_sel:WORD_1
	v_pk_fma_f32 v[202:203], v[174:175], v[218:219], v[202:203] op_sel:[1,0,0]
	v_pk_fma_f32 v[204:205], v[174:175], v[220:221], v[204:205] op_sel:[1,0,0]
	v_cvt_pk_f32_fp8_e32 v[214:215], v102
	v_cvt_pk_f32_fp8_sdwa v[216:217], v102 src0_sel:WORD_1
	v_pk_fma_f32 v[206:207], v[174:175], v[214:215], v[206:207] op_sel:[1,0,0]
	v_pk_fma_f32 v[208:209], v[174:175], v[216:217], v[208:209] op_sel:[1,0,0]
	v_cvt_pk_f32_fp8_e32 v[218:219], v103
	v_cvt_pk_f32_fp8_sdwa v[220:221], v103 src0_sel:WORD_1
	v_pk_fma_f32 v[210:211], v[174:175], v[218:219], v[210:211] op_sel:[1,0,0]
	v_pk_fma_f32 v[212:213], v[174:175], v[220:221], v[212:213] op_sel:[1,0,0]
	s_waitcnt lgkmcnt(0)
	v_lshl_add_u32 v170, v170, 8, v138
	v_lshl_add_u32 v171, v171, 8, v138
	v_lshl_add_u32 v172, v172, 8, v138
	v_lshl_add_u32 v173, v173, 8, v138
	buffer_load_dwordx4 v[80:83], v170, s[16:19], s26 offen sc0
	buffer_load_dwordx4 v[84:87], v171, s[16:19], s26 offen sc0
	buffer_load_dwordx4 v[88:91], v172, s[16:19], s26 offen sc0
	buffer_load_dwordx4 v[92:95], v173, s[16:19], s26 offen sc0
	s_waitcnt vmcnt(29)
	v_cvt_pk_f32_fp8_e32 v[214:215], v104
	v_cvt_pk_f32_fp8_sdwa v[216:217], v104 src0_sel:WORD_1
	v_pk_fma_f32 v[198:199], v[176:177], v[214:215], v[198:199] op_sel_hi:[0,1,1]
	v_pk_fma_f32 v[200:201], v[176:177], v[216:217], v[200:201] op_sel_hi:[0,1,1]
	v_cvt_pk_f32_fp8_e32 v[218:219], v105
	v_cvt_pk_f32_fp8_sdwa v[220:221], v105 src0_sel:WORD_1
	v_pk_fma_f32 v[202:203], v[176:177], v[218:219], v[202:203] op_sel_hi:[0,1,1]
	v_pk_fma_f32 v[204:205], v[176:177], v[220:221], v[204:205] op_sel_hi:[0,1,1]
	v_cvt_pk_f32_fp8_e32 v[214:215], v106
	v_cvt_pk_f32_fp8_sdwa v[216:217], v106 src0_sel:WORD_1
	v_pk_fma_f32 v[206:207], v[176:177], v[214:215], v[206:207] op_sel_hi:[0,1,1]
	v_pk_fma_f32 v[208:209], v[176:177], v[216:217], v[208:209] op_sel_hi:[0,1,1]
	v_cvt_pk_f32_fp8_e32 v[218:219], v107
	v_cvt_pk_f32_fp8_sdwa v[220:221], v107 src0_sel:WORD_1
	v_pk_fma_f32 v[210:211], v[176:177], v[218:219], v[210:211] op_sel_hi:[0,1,1]
	v_pk_fma_f32 v[212:213], v[176:177], v[220:221], v[212:213] op_sel_hi:[0,1,1]
	s_waitcnt vmcnt(28)
	v_cvt_pk_f32_fp8_e32 v[214:215], v108
	v_cvt_pk_f32_fp8_sdwa v[216:217], v108 src0_sel:WORD_1
	v_pk_fma_f32 v[198:199], v[176:177], v[214:215], v[198:199] op_sel:[1,0,0]
	v_pk_fma_f32 v[200:201], v[176:177], v[216:217], v[200:201] op_sel:[1,0,0]
	v_cvt_pk_f32_fp8_e32 v[218:219], v109
	v_cvt_pk_f32_fp8_sdwa v[220:221], v109 src0_sel:WORD_1
	v_pk_fma_f32 v[202:203], v[176:177], v[218:219], v[202:203] op_sel:[1,0,0]
	v_pk_fma_f32 v[204:205], v[176:177], v[220:221], v[204:205] op_sel:[1,0,0]
	v_cvt_pk_f32_fp8_e32 v[214:215], v110
	v_cvt_pk_f32_fp8_sdwa v[216:217], v110 src0_sel:WORD_1
	v_pk_fma_f32 v[206:207], v[176:177], v[214:215], v[206:207] op_sel:[1,0,0]
	v_pk_fma_f32 v[208:209], v[176:177], v[216:217], v[208:209] op_sel:[1,0,0]
	v_cvt_pk_f32_fp8_e32 v[218:219], v111
	v_cvt_pk_f32_fp8_sdwa v[220:221], v111 src0_sel:WORD_1
	v_pk_fma_f32 v[210:211], v[176:177], v[218:219], v[210:211] op_sel:[1,0,0]
	v_pk_fma_f32 v[212:213], v[176:177], v[220:221], v[212:213] op_sel:[1,0,0]
	ds_read_b128 v[174:177], v139 offset:96
	s_waitcnt vmcnt(27)
	v_cvt_pk_f32_fp8_e32 v[214:215], v112
	v_cvt_pk_f32_fp8_sdwa v[216:217], v112 src0_sel:WORD_1
	v_pk_fma_f32 v[198:199], v[178:179], v[214:215], v[198:199] op_sel_hi:[0,1,1]
	v_pk_fma_f32 v[200:201], v[178:179], v[216:217], v[200:201] op_sel_hi:[0,1,1]
	v_cvt_pk_f32_fp8_e32 v[218:219], v113
	v_cvt_pk_f32_fp8_sdwa v[220:221], v113 src0_sel:WORD_1
	v_pk_fma_f32 v[202:203], v[178:179], v[218:219], v[202:203] op_sel_hi:[0,1,1]
	v_pk_fma_f32 v[204:205], v[178:179], v[220:221], v[204:205] op_sel_hi:[0,1,1]
	v_cvt_pk_f32_fp8_e32 v[214:215], v114
	v_cvt_pk_f32_fp8_sdwa v[216:217], v114 src0_sel:WORD_1
	v_pk_fma_f32 v[206:207], v[178:179], v[214:215], v[206:207] op_sel_hi:[0,1,1]
	v_pk_fma_f32 v[208:209], v[178:179], v[216:217], v[208:209] op_sel_hi:[0,1,1]
	v_cvt_pk_f32_fp8_e32 v[218:219], v115
	v_cvt_pk_f32_fp8_sdwa v[220:221], v115 src0_sel:WORD_1
	v_pk_fma_f32 v[210:211], v[178:179], v[218:219], v[210:211] op_sel_hi:[0,1,1]
	v_pk_fma_f32 v[212:213], v[178:179], v[220:221], v[212:213] op_sel_hi:[0,1,1]
	s_waitcnt vmcnt(26)
; #define LAS __attribute__((address_space(3)))
; __device__ __forceinline__ void kv8_pv(const u32x4 (&buf)[8], f32x2v (&o2)[8], const LAS float* srow, int b) {
;     const LAS f32x4* p4 = (const LAS f32x4*)(srow + b * 8);
;     const f32x4 p0 = p4[0], p1 = p4[1];
;     const float p[8] = {p0.x, p0.y, p0.z, p0.w, p1.x, p1.y, p1.z, p1.w};
; #pragma unroll
;     for (int u = 0; u < 8; ++u) {
;         const u32x4 v = buf[u]; const f32x2v pp = {p[u], p[u]};
;         o2[0] = __builtin_elementwise_fma(pp, __builtin_amdgcn_cvt_pk_f32_fp8(v.x, false), o2[0]); o2[1] = __builtin_elementwise_fma(pp, __builtin_amdgcn_cvt_pk_f32_fp8(v.x, true), o2[1]);
;         o2[2] = __builtin_elementwise_fma(pp, __builtin_amdgcn_cvt_pk_f32_fp8(v.y, false), o2[2]); o2[3] = __builtin_elementwise_fma(pp, __builtin_amdgcn_cvt_pk_f32_fp8(v.y, true), o2[3]);
;         o2[4] = __builtin_elementwise_fma(pp, __builtin_amdgcn_cvt_pk_f32_fp8(v.z, false), o2[4]); o2[5] = __builtin_elementwise_fma(pp, __builtin_amdgcn_cvt_pk_f32_fp8(v.z, true), o2[5]);
;         o2[6] = __builtin_elementwise_fma(pp, __builtin_amdgcn_cvt_pk_f32_fp8(v.w, false), o2[6]); o2[7] = __builtin_elementwise_fma(pp, __builtin_amdgcn_cvt_pk_f32_fp8(v.w, true), o2[7]);
;     }
; __device__ __forceinline__ void attn_query8(const unsigned char* __restrict__ KV8, const bf16_t* __restrict__ Z, const int* __restrict__ SEL, bf16_t* __restrict__ YMIX, int t, LAS float* sbuf  ) {
;     ...
; #pragma unroll 1
;     for (int b = 0; b < nb; b += 3) {
;         kv8_issue(C, rs, lvo, 1024, iv, CLAMPB(b + 2));
;         kv8_pv(A, o, srow, b);
;         kv8_issue(A, rs, lvo, 1024, iv, CLAMPB(b + 3));
;         if (b + 1 < nb) kv8_pv(B, o, srow, b + 1);
;         kv8_issue(B, rs, lvo, 1024, iv, CLAMPB(b + 4));
;         if (b + 2 < nb) kv8_pv(C, o, srow, b + 2);
;     }
	v_cvt_pk_f32_fp8_e32 v[214:215], v116
	v_cvt_pk_f32_fp8_sdwa v[216:217], v116 src0_sel:WORD_1
	v_pk_fma_f32 v[198:199], v[178:179], v[214:215], v[198:199] op_sel:[1,0,0]
	v_pk_fma_f32 v[200:201], v[178:179], v[216:217], v[200:201] op_sel:[1,0,0]
	v_cvt_pk_f32_fp8_e32 v[218:219], v117
	v_cvt_pk_f32_fp8_sdwa v[220:221], v117 src0_sel:WORD_1
	v_pk_fma_f32 v[202:203], v[178:179], v[218:219], v[202:203] op_sel:[1,0,0]
	v_pk_fma_f32 v[204:205], v[178:179], v[220:221], v[204:205] op_sel:[1,0,0]
	v_cvt_pk_f32_fp8_e32 v[214:215], v118
	v_cvt_pk_f32_fp8_sdwa v[216:217], v118 src0_sel:WORD_1
	v_pk_fma_f32 v[206:207], v[178:179], v[214:215], v[206:207] op_sel:[1,0,0]
	v_pk_fma_f32 v[208:209], v[178:179], v[216:217], v[208:209] op_sel:[1,0,0]
	v_cvt_pk_f32_fp8_e32 v[218:219], v119
	v_cvt_pk_f32_fp8_sdwa v[220:221], v119 src0_sel:WORD_1
	v_pk_fma_f32 v[210:211], v[178:179], v[218:219], v[210:211] op_sel:[1,0,0]
	v_pk_fma_f32 v[212:213], v[178:179], v[220:221], v[212:213] op_sel:[1,0,0]
	s_waitcnt lgkmcnt(0)
	v_lshl_add_u32 v174, v174, 8, v138
	v_lshl_add_u32 v175, v175, 8, v138
	v_lshl_add_u32 v176, v176, 8, v138
	v_lshl_add_u32 v177, v177, 8, v138
	buffer_load_dwordx4 v[96:99], v174, s[16:19], s26 offen sc0
	buffer_load_dwordx4 v[100:103], v175, s[16:19], s26 offen sc0
	buffer_load_dwordx4 v[104:107], v176, s[16:19], s26 offen sc0
	buffer_load_dwordx4 v[108:111], v177, s[16:19], s26 offen sc0
	s_waitcnt vmcnt(29)
	v_cvt_pk_f32_fp8_e32 v[214:215], v120
	v_cvt_pk_f32_fp8_sdwa v[216:217], v120 src0_sel:WORD_1
	v_pk_fma_f32 v[198:199], v[180:181], v[214:215], v[198:199] op_sel_hi:[0,1,1]
	v_pk_fma_f32 v[200:201], v[180:181], v[216:217], v[200:201] op_sel_hi:[0,1,1]
	v_cvt_pk_f32_fp8_e32 v[218:219], v121
	v_cvt_pk_f32_fp8_sdwa v[220:221], v121 src0_sel:WORD_1
	v_pk_fma_f32 v[202:203], v[180:181], v[218:219], v[202:203] op_sel_hi:[0,1,1]
	v_pk_fma_f32 v[204:205], v[180:181], v[220:221], v[204:205] op_sel_hi:[0,1,1]
	v_cvt_pk_f32_fp8_e32 v[214:215], v122
	v_cvt_pk_f32_fp8_sdwa v[216:217], v122 src0_sel:WORD_1
	v_pk_fma_f32 v[206:207], v[180:181], v[214:215], v[206:207] op_sel_hi:[0,1,1]
	v_pk_fma_f32 v[208:209], v[180:181], v[216:217], v[208:209] op_sel_hi:[0,1,1]
	v_cvt_pk_f32_fp8_e32 v[218:219], v123
	v_cvt_pk_f32_fp8_sdwa v[220:221], v123 src0_sel:WORD_1
	v_pk_fma_f32 v[210:211], v[180:181], v[218:219], v[210:211] op_sel_hi:[0,1,1]
	v_pk_fma_f32 v[212:213], v[180:181], v[220:221], v[212:213] op_sel_hi:[0,1,1]
	s_waitcnt vmcnt(28)
	v_cvt_pk_f32_fp8_e32 v[214:215], v124
	v_cvt_pk_f32_fp8_sdwa v[216:217], v124 src0_sel:WORD_1
	v_pk_fma_f32 v[198:199], v[180:181], v[214:215], v[198:199] op_sel:[1,0,0]
	v_pk_fma_f32 v[200:201], v[180:181], v[216:217], v[200:201] op_sel:[1,0,0]
	v_cvt_pk_f32_fp8_e32 v[218:219], v125
	v_cvt_pk_f32_fp8_sdwa v[220:221], v125 src0_sel:WORD_1
	v_pk_fma_f32 v[202:203], v[180:181], v[218:219], v[202:203] op_sel:[1,0,0]
	v_pk_fma_f32 v[204:205], v[180:181], v[220:221], v[204:205] op_sel:[1,0,0]
	v_cvt_pk_f32_fp8_e32 v[214:215], v126
	v_cvt_pk_f32_fp8_sdwa v[216:217], v126 src0_sel:WORD_1
	v_pk_fma_f32 v[206:207], v[180:181], v[214:215], v[206:207] op_sel:[1,0,0]
	v_pk_fma_f32 v[208:209], v[180:181], v[216:217], v[208:209] op_sel:[1,0,0]
	v_cvt_pk_f32_fp8_e32 v[218:219], v127
	v_cvt_pk_f32_fp8_sdwa v[220:221], v127 src0_sel:WORD_1
	v_pk_fma_f32 v[210:211], v[180:181], v[218:219], v[210:211] op_sel:[1,0,0]
	v_pk_fma_f32 v[212:213], v[180:181], v[220:221], v[212:213] op_sel:[1,0,0]
	ds_read_b128 v[178:181], v139 offset:112
	v_add_f32_dpp v198, v198, v198 row_ror:8 row_mask:0xf bank_mask:0xf
	v_add_f32_dpp v199, v199, v199 row_ror:8 row_mask:0xf bank_mask:0xf
	v_add_f32_dpp v200, v200, v200 row_ror:8 row_mask:0xf bank_mask:0xf
	v_add_f32_dpp v201, v201, v201 row_ror:8 row_mask:0xf bank_mask:0xf
	v_add_f32_dpp v202, v202, v202 row_ror:8 row_mask:0xf bank_mask:0xf
	v_add_f32_dpp v203, v203, v203 row_ror:8 row_mask:0xf bank_mask:0xf
	v_add_f32_dpp v204, v204, v204 row_ror:8 row_mask:0xf bank_mask:0xf
	v_add_f32_dpp v205, v205, v205 row_ror:8 row_mask:0xf bank_mask:0xf
	v_add_f32_dpp v206, v206, v206 row_ror:8 row_mask:0xf bank_mask:0xf
	v_add_f32_dpp v207, v207, v207 row_ror:8 row_mask:0xf bank_mask:0xf
	v_add_f32_dpp v208, v208, v208 row_ror:8 row_mask:0xf bank_mask:0xf
	v_add_f32_dpp v209, v209, v209 row_ror:8 row_mask:0xf bank_mask:0xf
	v_add_f32_dpp v210, v210, v210 row_ror:8 row_mask:0xf bank_mask:0xf
	v_add_f32_dpp v211, v211, v211 row_ror:8 row_mask:0xf bank_mask:0xf
	v_add_f32_dpp v212, v212, v212 row_ror:8 row_mask:0xf bank_mask:0xf
	v_add_f32_dpp v213, v213, v213 row_ror:8 row_mask:0xf bank_mask:0xf
	s_waitcnt lgkmcnt(0)
; __device__ __forceinline__ unsigned cvt_pk_bf16(float lo, float hi) { unsigned r; asm volatile("v_cvt_pk_bf16_f32 %0, %1, %2" : "=v"(r) : "v"(lo), "v"(hi)); return r; }
; #define LDS_WAIT() asm volatile("s_waitcnt lgkmcnt(0)" ::: "memory")
; __device__ __forceinline__ void kv8_issue(u32x4 (&buf)[8], __amdgpu_buffer_rsrc_t rs, int voff  , int sbase  , const int (&iv)[4], int b) {
;     ...
;     for (int u = 0; u < 8; ++u) { const int si = __builtin_amdgcn_readlane(ivb, l0 + u); buf[u] = __builtin_amdgcn_raw_buffer_load_b128(rs, voff, si * 2048 + sbase, KV8_AUX); }
; __device__ __forceinline__ void attn_query8(const unsigned char* __restrict__ KV8, const bf16_t* __restrict__ Z, const int* __restrict__ SEL, bf16_t* __restrict__ YMIX, int t, LAS float* sbuf  ) {
;     ...
;     u32x4 o0, o1;
;     o0.x = cvt_pk_bf16(o[0].x, o[0].y); o0.y = cvt_pk_bf16(o[1].x, o[1].y); o0.z = cvt_pk_bf16(o[2].x, o[2].y); o0.w = cvt_pk_bf16(o[3].x, o[3].y);
;     o1.x = cvt_pk_bf16(o[4].x, o[4].y); o1.y = cvt_pk_bf16(o[5].x, o[5].y); o1.z = cvt_pk_bf16(o[6].x, o[6].y); o1.w = cvt_pk_bf16(o[7].x, o[7].y);
;     u32x4* yp = (u32x4*)(YMIX + (size_t)t * D_ + 1024 + lane * 16);
;     yp[0] = o0; yp[1] = o1;
;     LDS_WAIT();
	v_lshl_add_u32 v178, v178, 8, v138
	v_lshl_add_u32 v179, v179, 8, v138
	v_lshl_add_u32 v180, v180, 8, v138
	v_lshl_add_u32 v181, v181, 8, v138
	buffer_load_dwordx4 v[112:115], v178, s[16:19], s26 offen sc0
	buffer_load_dwordx4 v[116:119], v179, s[16:19], s26 offen sc0
	buffer_load_dwordx4 v[120:123], v180, s[16:19], s26 offen sc0
	buffer_load_dwordx4 v[124:127], v181, s[16:19], s26 offen sc0
	ds_bpermute_b32 v214, v140, v198
	ds_bpermute_b32 v215, v140, v199
	ds_bpermute_b32 v216, v140, v200
	ds_bpermute_b32 v217, v140, v201
	ds_bpermute_b32 v218, v140, v202
	ds_bpermute_b32 v219, v140, v203
	ds_bpermute_b32 v220, v140, v204
	ds_bpermute_b32 v221, v140, v205
	ds_bpermute_b32 v222, v140, v206
	ds_bpermute_b32 v223, v140, v207
	ds_bpermute_b32 v224, v140, v208
	ds_bpermute_b32 v225, v140, v209
	ds_bpermute_b32 v226, v140, v210
	ds_bpermute_b32 v227, v140, v211
	ds_bpermute_b32 v228, v140, v212
	ds_bpermute_b32 v229, v140, v213
	s_waitcnt lgkmcnt(0)
	v_add_f32_e32 v198, v198, v214
	v_add_f32_e32 v199, v199, v215
	v_add_f32_e32 v200, v200, v216
	v_add_f32_e32 v201, v201, v217
	v_add_f32_e32 v202, v202, v218
	v_add_f32_e32 v203, v203, v219
	v_add_f32_e32 v204, v204, v220
	v_add_f32_e32 v205, v205, v221
	v_add_f32_e32 v206, v206, v222
	v_add_f32_e32 v207, v207, v223
	v_add_f32_e32 v208, v208, v224
	v_add_f32_e32 v209, v209, v225
	v_add_f32_e32 v210, v210, v226
	v_add_f32_e32 v211, v211, v227
	v_add_f32_e32 v212, v212, v228
	v_add_f32_e32 v213, v213, v229
	ds_bpermute_b32 v214, v141, v198
	ds_bpermute_b32 v215, v141, v199
	ds_bpermute_b32 v216, v141, v200
	ds_bpermute_b32 v217, v141, v201
	ds_bpermute_b32 v218, v141, v202
	ds_bpermute_b32 v219, v141, v203
	ds_bpermute_b32 v220, v141, v204
	ds_bpermute_b32 v221, v141, v205
	ds_bpermute_b32 v222, v141, v206
	ds_bpermute_b32 v223, v141, v207
	ds_bpermute_b32 v224, v141, v208
	ds_bpermute_b32 v225, v141, v209
	ds_bpermute_b32 v226, v141, v210
	ds_bpermute_b32 v227, v141, v211
	ds_bpermute_b32 v228, v141, v212
	ds_bpermute_b32 v229, v141, v213
	s_waitcnt lgkmcnt(0)
	v_add_f32_e32 v198, v198, v214
	v_add_f32_e32 v199, v199, v215
	v_add_f32_e32 v200, v200, v216
	v_add_f32_e32 v201, v201, v217
	v_add_f32_e32 v202, v202, v218
	v_add_f32_e32 v203, v203, v219
	v_add_f32_e32 v204, v204, v220
	v_add_f32_e32 v205, v205, v221
	v_add_f32_e32 v206, v206, v222
	v_add_f32_e32 v207, v207, v223
	v_add_f32_e32 v208, v208, v224
	v_add_f32_e32 v209, v209, v225
	v_add_f32_e32 v210, v210, v226
	v_add_f32_e32 v211, v211, v227
	v_add_f32_e32 v212, v212, v228
	v_add_f32_e32 v213, v213, v229
	s_ashr_i32 s81, s80, 31
	s_lshl_b64 s[10:11], s[80:81], 12
	s_add_u32 s10, s14, s10
	s_addc_u32 s11, s15, s11
	v_mul_f32_e32 v198, v198, v149
	v_mul_f32_e32 v199, v199, v149
	v_mul_f32_e32 v200, v200, v149
	v_mul_f32_e32 v201, v201, v149
	v_mul_f32_e32 v202, v202, v149
	v_mul_f32_e32 v203, v203, v149
	v_mul_f32_e32 v204, v204, v149
	v_mul_f32_e32 v205, v205, v149
	v_mul_f32_e32 v206, v206, v149
	v_mul_f32_e32 v207, v207, v149
	v_mul_f32_e32 v208, v208, v149
	v_mul_f32_e32 v209, v209, v149
	v_mul_f32_e32 v210, v210, v149
	v_mul_f32_e32 v211, v211, v149
	v_mul_f32_e32 v212, v212, v149
	v_mul_f32_e32 v213, v213, v149
	v_cvt_pk_bf16_f32 v214, v198, v199
	v_cvt_pk_bf16_f32 v215, v200, v201
	v_cvt_pk_bf16_f32 v216, v202, v203
	v_cvt_pk_bf16_f32 v217, v204, v205
	v_cvt_pk_bf16_f32 v218, v206, v207
	v_cvt_pk_bf16_f32 v219, v208, v209
	v_cvt_pk_bf16_f32 v220, v210, v211
	v_cvt_pk_bf16_f32 v221, v212, v213
	v_cmp_gt_u32_e32 vcc, 8, v144
	s_and_saveexec_b64 s[12:13], vcc
	global_store_dwordx4 v146, v[214:217], s[10:11] offset:2048
	global_store_dwordx4 v146, v[218:221], s[10:11] offset:2064
	s_mov_b64 exec, s[12:13]
	s_addk_i32 s80, 0x100
	s_cmpk_gt_i32 s80, 0x3fff
	s_cbranch_scc0 .Latt_unit
	s_waitcnt vmcnt(0)
